# stacked: QK reference fold + LoRA deferred prefetch and hoisted bias loads + weight-conversion touch-prefetch, on top of the once-per-iteration attention reference update
# speedup vs baseline: 1.0009x; 1.0009x over previous
; DEV float sigmoidf_(float x) { return __builtin_amdgcn_rcpf(1.f + __expf(-x)); }
; DEV void lora64_phase(const Params& p, int l, char* smem) {
;     ...
;     if (L + (int)gridDim.x < 4 * 544) issue(L + gridDim.x);
;     f32x4 acc[4][4];
;     zero_acc(acc);
; #pragma unroll
;     for (int ks = 0; ks < 2; ++ks) {
;       bf16x8 af[4], bfr[4];
; #pragma unroll
;       for (int mi = 0; mi < 4; ++mi) af[mi] = *(const bf16x8*)(sra + mi * 16 * SROW + ks * 64);
; #pragma unroll
;       for (int ni = 0; ni < 4; ++ni) bfr[ni] = *(const bf16x8*)(srb + ni * 16 * SROW + ks * 64);
; #pragma unroll
;       for (int mi = 0; mi < 4; ++mi)
; #pragma unroll
;         for (int ni = 0; ni < 4; ++ni) acc[mi][ni] = __builtin_amdgcn_mfma_f32_16x16x32_bf16(bfr[ni], af[mi], acc[mi][ni], 0, 0, 0);
;     }
;     bf16_t* O = (bf16_t*)(p.ws + (job == 0 ? O_EF : (job == 1 ? O_EB : (job == 2 ? O_AF : O_AB))));
;     const float* bias = ((job & 2) ? p.rwkv_a0 : p.rwkv_w0) + (l * 2 + (job & 1)) * 512;
;     const float sc = job < 2 ? 0.6065306597126334f : 1.f;
;     f32x4 bv[4];
; #pragma unroll
;     for (int ni = 0; ni < 4; ++ni) bv[ni] = *(const f32x4*)(bias + col0 + wn * 64 + ni * 16 + fq * 4);
; #pragma unroll
;     for (int mi = 0; mi < 4; ++mi) {
;       const int row = row0 + wm * 64 + mi * 16 + fr;
; #pragma unroll
;       for (int ni = 0; ni < 4; ++ni) {
;         const int c = col0 + wn * 64 + ni * 16 + fq * 4;
;         const f32x4 z = acc[mi][ni] + bv[ni];
;         uint2 o;
;         o.x = pk2(sc * sigmoidf_(z[0]), sc * sigmoidf_(z[1])); o.y = pk2(sc * sigmoidf_(z[2]), sc * sigmoidf_(z[3]));
;         *(uint2*)(O + (size_t)row * 512 + c) = o;
;       }
.LBB0_210:
	s_mul_hi_i32 s31, s30, 0x78787879
	s_lshr_b32 s40, s31, 31
	s_ashr_i32 s31, s31, 8
	s_add_i32 s31, s31, s40
	v_readlane_b32 s41, v254, 45
	s_mul_i32 s40, s31, 0xffff7800
	s_add_i32 s41, s41, s38
	s_add_i32 s41, s41, s40
	v_readlane_b32 s40, v254, 47
	s_add_i32 s40, s40, s37
	s_and_b32 s41, s41, 0xffffff00
	s_and_b32 s40, s40, 0x180
	s_add_i32 s42, s30, 0x21f
	s_add_i32 s43, s30, 0xfffffde0
	s_add_i32 s44, s30, 0xfffffbc0
	s_cmpk_lt_u32 s44, 0x220
	s_mov_b32 s44, 0xaa00000
	s_cselect_b32 s44, 0x8800000, s44
	s_cmpk_gt_u32 s43, 0x21f
	s_cselect_b32 s43, s44, 0x6600000
	s_cmpk_gt_u32 s42, 0x43e
	v_readlane_b32 s56, v251, 21
	s_cselect_b32 s44, s43, 0
	s_bitcmp0_b32 s31, 1
	v_readlane_b32 s66, v251, 31
	v_readlane_b32 s67, v251, 32
	v_readlane_b32 s70, v251, 35
	v_readlane_b32 s71, v251, 36
	s_cselect_b32 s45, s67, s71
	s_cselect_b32 s46, s66, s70
	s_lshl_b32 s31, s31, 9
	ds_read_b128 v[24:27], v117
	ds_read_b128 v[28:31], v117 offset:2304
	ds_read_b128 v[32:35], v117 offset:4608
	ds_read_b128 v[36:39], v117 offset:6912
	ds_read_b128 v[40:43], v118 offset:36864
	ds_read_b128 v[44:47], v118 offset:39168
	ds_read_b128 v[48:51], v118 offset:41472
	ds_read_b128 v[52:55], v118 offset:43776
	s_and_b32 s31, s31, 0x200
	s_or_b32 s42, s31, s36
	s_ashr_i32 s43, s42, 31
	s_lshl_b64 s[42:43], s[42:43], 2
	s_add_u32 s31, s46, s42
	s_waitcnt lgkmcnt(3)
	v_mfma_f32_16x16x32_bf16 v[56:59], v[40:43], v[24:27], 0
	s_addc_u32 s42, s45, s43
	s_cmpk_lt_i32 s30, 0x440
	s_cselect_b64 vcc, -1, 0
	s_waitcnt lgkmcnt(2)
	v_mfma_f32_16x16x32_bf16 v[60:63], v[44:47], v[24:27], 0
	s_lshl_b32 s30, s40, 2
	s_add_u32 s30, s31, s30
	s_addc_u32 s31, s42, 0
	s_waitcnt lgkmcnt(1)
	v_mfma_f32_16x16x32_bf16 v[64:67], v[48:51], v[24:27], 0
	v_mov_b32_e32 v109, v97
	v_lshl_add_u64 v[176:177], s[30:31], 0, v[96:97]
	v_lshl_add_u64 v[176:177], v[176:177], 0, v[108:109]
	global_load_dwordx4 v[160:163], v[176:177], off
	global_load_dwordx4 v[164:167], v[176:177], off offset:64
	global_load_dwordx4 v[168:171], v[176:177], off offset:128
	global_load_dwordx4 v[172:175], v[176:177], off offset:192
	v_mov_b32_e32 v107, 0x3f1b4598
	v_cndmask_b32_e32 v110, 1.0, v107, vcc
	s_waitcnt lgkmcnt(0)
	v_mfma_f32_16x16x32_bf16 v[24:27], v[52:55], v[24:27], 0
	v_add_u32_e32 v112, s41, v114
	v_ashrrev_i32_e32 v113, 31, v112
	v_or_b32_e32 v107, s40, v115
	v_mfma_f32_16x16x32_bf16 v[68:71], v[40:43], v[28:31], 0
	v_readlane_b32 s70, v255, 41
	v_readlane_b32 s57, v251, 22
	v_readlane_b32 s58, v251, 23
	v_mfma_f32_16x16x32_bf16 v[72:75], v[44:47], v[28:31], 0
	v_readlane_b32 s59, v251, 24
	v_readlane_b32 s60, v251, 25
	v_readlane_b32 s61, v251, 26
	v_mfma_f32_16x16x32_bf16 v[76:79], v[48:51], v[28:31], 0
	v_readlane_b32 s62, v251, 27
	v_readlane_b32 s63, v251, 28
	v_readlane_b32 s64, v251, 29
	v_mfma_f32_16x16x32_bf16 v[28:31], v[52:55], v[28:31], 0
	v_readlane_b32 s65, v251, 30
	v_readlane_b32 s68, v251, 33
	v_readlane_b32 s69, v251, 34
	v_mfma_f32_16x16x32_bf16 v[120:123], v[40:43], v[32:35], 0
	v_mfma_f32_16x16x32_bf16 v[124:127], v[44:47], v[32:35], 0
	v_mfma_f32_16x16x32_bf16 v[128:131], v[48:51], v[32:35], 0
	v_mfma_f32_16x16x32_bf16 v[32:35], v[52:55], v[32:35], 0
	v_mfma_f32_16x16x32_bf16 v[40:43], v[40:43], v[36:39], 0
	v_mfma_f32_16x16x32_bf16 v[44:47], v[44:47], v[36:39], 0
	v_mfma_f32_16x16x32_bf16 v[132:135], v[48:51], v[36:39], 0
	v_mfma_f32_16x16x32_bf16 v[36:39], v[52:55], v[36:39], 0
	ds_read_b128 v[48:51], v117 offset:64
	ds_read_b128 v[52:55], v117 offset:2368
	ds_read_b128 v[136:139], v117 offset:4672
	ds_read_b128 v[140:143], v117 offset:6976
	ds_read_b128 v[144:147], v118 offset:36928
	ds_read_b128 v[148:151], v118 offset:39232
	ds_read_b128 v[152:155], v118 offset:41536
	ds_read_b128 v[156:159], v118 offset:43840
	s_waitcnt lgkmcnt(0)
	v_mfma_f32_16x16x32_bf16 v[88:91], v[156:159], v[48:51], v[24:27]
	v_mfma_f32_16x16x32_bf16 v[24:27], v[156:159], v[140:143], v[36:39]
	s_nop 2
	v_mfma_f32_16x16x32_bf16 v[102:105], v[144:147], v[48:51], v[56:59]
	s_add_u32 s30, s74, s44
	s_addc_u32 s31, s75, 0
	s_add_i32 s38, s38, s33
	v_mfma_f32_16x16x32_bf16 v[98:101], v[148:151], v[48:51], v[60:63]
	s_add_i32 s37, s37, s70
	s_andn2_b64 vcc, exec, s[0:1]
	v_mfma_f32_16x16x32_bf16 v[92:95], v[152:155], v[48:51], v[64:67]
	v_mfma_f32_16x16x32_bf16 v[84:87], v[144:147], v[52:55], v[68:71]
	v_mfma_f32_16x16x32_bf16 v[80:83], v[148:151], v[52:55], v[72:75]
	v_mfma_f32_16x16x32_bf16 v[76:79], v[152:155], v[52:55], v[76:79]
	v_mfma_f32_16x16x32_bf16 v[72:75], v[156:159], v[52:55], v[28:31]
	v_mfma_f32_16x16x32_bf16 v[48:51], v[156:159], v[136:139], v[32:35]
	v_mfma_f32_16x16x32_bf16 v[32:35], v[148:151], v[140:143], v[44:47]
	s_waitcnt vmcnt(3)
	v_pk_add_f32 v[102:103], v[102:103], v[160:161]
	s_nop 0
	v_mul_f32_e32 v102, 0xbfb8aa3b, v102
	v_mul_f32_e32 v103, 0xbfb8aa3b, v103
	s_waitcnt vmcnt(0)
	s_cbranch_vccz .Llora_nopf
	global_load_dwordx4 v[0:3], v[8:9], off
	global_load_dwordx4 v[4:7], v[4:5], off
	global_load_dwordx4 v[8:11], v[10:11], off
	global_load_dwordx4 v[12:15], v[12:13], off
	global_load_dwordx4 v[16:19], v[16:17], off
	global_load_dwordx4 v[20:23], v[20:21], off
; DEV float sigmoidf_(float x) { return __builtin_amdgcn_rcpf(1.f + __expf(-x)); }
; DEV void lora64_phase(const Params& p, int l, char* smem) {
;     ...
;     for (int mi = 0; mi < 4; ++mi) {
;       const int row = row0 + wm * 64 + mi * 16 + fr;
; #pragma unroll
;       for (int ni = 0; ni < 4; ++ni) {
;         const int c = col0 + wn * 64 + ni * 16 + fq * 4;
;         const f32x4 z = acc[mi][ni] + bv[ni];
;         uint2 o;
;         o.x = pk2(sc * sigmoidf_(z[0]), sc * sigmoidf_(z[1])); o.y = pk2(sc * sigmoidf_(z[2]), sc * sigmoidf_(z[3]));
;         *(uint2*)(O + (size_t)row * 512 + c) = o;
;       }
.Llora_nopf:
	v_pk_add_f32 v[88:89], v[88:89], v[172:173]
	v_pk_add_f32 v[72:73], v[72:73], v[172:173]
	v_mul_f32_e32 v88, 0xbfb8aa3b, v88
	v_mul_f32_e32 v89, 0xbfb8aa3b, v89
	v_exp_f32_e32 v88, v88
	v_exp_f32_e32 v89, v89
	v_mul_f32_e32 v72, 0xbfb8aa3b, v72
	v_mul_f32_e32 v73, 0xbfb8aa3b, v73
	v_add_f32_e32 v88, 1.0, v88
	v_add_f32_e32 v89, 1.0, v89
	v_rcp_f32_e32 v88, v88
	v_rcp_f32_e32 v89, v89
	v_exp_f32_e32 v72, v72
	v_exp_f32_e32 v73, v73
	v_pk_add_f32 v[48:49], v[48:49], v[172:173]
	v_pk_add_f32 v[90:91], v[90:91], v[174:175]
	v_pk_mul_f32 v[88:89], v[110:111], v[88:89] op_sel_hi:[0,1]
	v_add_f32_e32 v72, 1.0, v72
	v_add_f32_e32 v73, 1.0, v73
	v_mul_f32_e32 v48, 0xbfb8aa3b, v48
	v_mul_f32_e32 v49, 0xbfb8aa3b, v49
	v_cvt_pk_bf16_f32 v88, v88, v89
	v_mul_f32_e32 v89, 0xbfb8aa3b, v90
	v_rcp_f32_e32 v72, v72
	v_rcp_f32_e32 v73, v73
	v_exp_f32_e32 v48, v48
	v_exp_f32_e32 v49, v49
	v_exp_f32_e32 v102, v102
	v_exp_f32_e32 v103, v103
	v_exp_f32_e32 v89, v89
	v_pk_add_f32 v[74:75], v[74:75], v[174:175]
	v_pk_mul_f32 v[72:73], v[110:111], v[72:73] op_sel_hi:[0,1]
	v_add_f32_e32 v48, 1.0, v48
	v_add_f32_e32 v49, 1.0, v49
	v_mfma_f32_16x16x32_bf16 v[64:67], v[148:151], v[136:139], v[124:127]
	v_add_f32_e32 v102, 1.0, v102
	v_add_f32_e32 v103, 1.0, v103
	v_add_f32_e32 v89, 1.0, v89
	v_mfma_f32_16x16x32_bf16 v[56:59], v[152:155], v[136:139], v[128:131]
	v_add_f32_e64 v84, v84, v160
	v_add_f32_e64 v85, v85, v161
	v_cvt_pk_bf16_f32 v72, v72, v73
	v_mul_f32_e32 v73, 0xbfb8aa3b, v74
	v_mfma_f32_16x16x32_bf16 v[28:31], v[152:155], v[140:143], v[132:135]
	v_rcp_f32_e32 v48, v48
	v_rcp_f32_e32 v49, v49
	v_rcp_f32_e32 v102, v102
	v_mfma_f32_16x16x32_bf16 v[68:71], v[144:147], v[136:139], v[120:123]
	v_rcp_f32_e32 v103, v103
	v_rcp_f32_e32 v90, v89
	v_mul_f32_e32 v89, 0xbfb8aa3b, v91
	v_mul_f32_e32 v84, 0xbfb8aa3b, v84
	v_mul_f32_e32 v85, 0xbfb8aa3b, v85
	v_exp_f32_e32 v73, v73
	v_exp_f32_e32 v89, v89
	v_exp_f32_e32 v84, v84
	v_exp_f32_e32 v85, v85
	v_pk_add_f32 v[98:99], v[98:99], v[164:165]
	v_pk_add_f32 v[92:93], v[92:93], v[168:169]
	v_pk_add_f32 v[80:81], v[80:81], v[164:165]
	v_pk_add_f32 v[76:77], v[76:77], v[168:169]
	v_pk_add_f32 v[64:65], v[64:65], v[164:165]
	v_pk_add_f32 v[56:57], v[56:57], v[168:169]
	v_pk_add_f32 v[50:51], v[50:51], v[174:175]
	v_pk_mul_f32 v[48:49], v[110:111], v[48:49] op_sel_hi:[0,1]
	v_pk_add_f32 v[32:33], v[32:33], v[164:165]
	v_pk_add_f32 v[28:29], v[28:29], v[168:169]
	v_pk_add_f32 v[24:25], v[24:25], v[172:173]
	v_pk_add_f32 v[104:105], v[104:105], v[162:163]
	v_pk_mul_f32 v[102:103], v[110:111], v[102:103] op_sel_hi:[0,1]
	v_mul_f32_e32 v98, 0xbfb8aa3b, v98
	v_mul_f32_e32 v99, 0xbfb8aa3b, v99
	v_mul_f32_e32 v92, 0xbfb8aa3b, v92
	v_mul_f32_e32 v93, 0xbfb8aa3b, v93
	v_mul_f32_e32 v80, 0xbfb8aa3b, v80
	v_mul_f32_e32 v81, 0xbfb8aa3b, v81
	v_mul_f32_e32 v76, 0xbfb8aa3b, v76
	v_mul_f32_e32 v77, 0xbfb8aa3b, v77
	v_add_f32_e32 v73, 1.0, v73
	v_pk_add_f32 v[68:69], v[68:69], v[160:161]
	v_mul_f32_e32 v64, 0xbfb8aa3b, v64
	v_mul_f32_e32 v65, 0xbfb8aa3b, v65
	v_mul_f32_e32 v56, 0xbfb8aa3b, v56
	v_mul_f32_e32 v57, 0xbfb8aa3b, v57
	v_cvt_pk_bf16_f32 v48, v48, v49
	v_mul_f32_e32 v49, 0xbfb8aa3b, v50
	v_mul_f32_e32 v32, 0xbfb8aa3b, v32
	v_mul_f32_e32 v33, 0xbfb8aa3b, v33
	v_mul_f32_e32 v28, 0xbfb8aa3b, v28
	v_mul_f32_e32 v29, 0xbfb8aa3b, v29
	v_mul_f32_e32 v24, 0xbfb8aa3b, v24
	v_mul_f32_e32 v25, 0xbfb8aa3b, v25
	v_mfma_f32_16x16x32_bf16 v[40:43], v[144:147], v[140:143], v[40:43]
	v_cvt_pk_bf16_f32 v122, v102, v103
	v_mul_f32_e32 v102, 0xbfb8aa3b, v104
	v_mul_f32_e32 v103, 0xbfb8aa3b, v105
	v_exp_f32_e32 v98, v98
	v_exp_f32_e32 v99, v99
	v_exp_f32_e32 v92, v92
	v_exp_f32_e32 v93, v93
	v_add_f32_e32 v89, 1.0, v89
	v_add_f32_e32 v84, 1.0, v84
	v_add_f32_e32 v85, 1.0, v85
	v_exp_f32_e32 v80, v80
	v_exp_f32_e32 v81, v81
	v_exp_f32_e32 v76, v76
	v_exp_f32_e32 v77, v77
	v_rcp_f32_e32 v74, v73
	v_mul_f32_e32 v73, 0xbfb8aa3b, v75
	v_mul_f32_e32 v68, 0xbfb8aa3b, v68
	v_mul_f32_e32 v69, 0xbfb8aa3b, v69
	v_exp_f32_e32 v64, v64
	v_exp_f32_e32 v65, v65
	v_exp_f32_e32 v56, v56
	v_exp_f32_e32 v57, v57
	v_exp_f32_e32 v49, v49
	v_exp_f32_e32 v32, v32
	v_exp_f32_e32 v33, v33
	v_exp_f32_e32 v28, v28
	v_exp_f32_e32 v29, v29
	v_exp_f32_e32 v24, v24
	v_exp_f32_e32 v25, v25
	v_exp_f32_e32 v102, v102
	v_exp_f32_e32 v103, v103
	v_rcp_f32_e32 v91, v89
	v_rcp_f32_e32 v84, v84
	v_rcp_f32_e32 v85, v85
	v_exp_f32_e32 v73, v73
	v_exp_f32_e32 v68, v68
	v_exp_f32_e32 v69, v69
	v_add_f32_e32 v98, 1.0, v98
	v_add_f32_e32 v99, 1.0, v99
	v_add_f32_e32 v92, 1.0, v92
	v_add_f32_e32 v93, 1.0, v93
	v_add_f32_e32 v80, 1.0, v80
	v_add_f32_e32 v81, 1.0, v81
	v_add_f32_e32 v76, 1.0, v76
	v_add_f32_e32 v77, 1.0, v77
	v_add_f32_e32 v64, 1.0, v64
	v_add_f32_e32 v65, 1.0, v65
	v_add_f32_e32 v56, 1.0, v56
	v_add_f32_e32 v57, 1.0, v57
	v_add_f32_e32 v49, 1.0, v49
	v_pk_add_f32 v[40:41], v[40:41], v[160:161]
	v_add_f32_e32 v32, 1.0, v32
	v_add_f32_e32 v33, 1.0, v33
	v_add_f32_e32 v28, 1.0, v28
	v_add_f32_e32 v29, 1.0, v29
	v_add_f32_e32 v24, 1.0, v24
	v_add_f32_e32 v25, 1.0, v25
	v_add_f32_e32 v102, 1.0, v102
	v_add_f32_e32 v103, 1.0, v103
	v_rcp_f32_e32 v98, v98
	v_rcp_f32_e32 v99, v99
	v_rcp_f32_e32 v92, v92
	v_rcp_f32_e32 v93, v93
	v_pk_mul_f32 v[90:91], v[110:111], v[90:91] op_sel_hi:[0,1]
	v_pk_add_f32 v[86:87], v[86:87], v[162:163]
	v_pk_mul_f32 v[84:85], v[110:111], v[84:85] op_sel_hi:[0,1]
	v_rcp_f32_e32 v80, v80
	v_rcp_f32_e32 v81, v81
	v_rcp_f32_e32 v76, v76
	v_rcp_f32_e32 v77, v77
	v_add_f32_e32 v73, 1.0, v73
	v_add_f32_e32 v68, 1.0, v68
	v_add_f32_e32 v69, 1.0, v69
	v_rcp_f32_e32 v64, v64
	v_rcp_f32_e32 v65, v65
	v_rcp_f32_e32 v56, v56
	v_rcp_f32_e32 v57, v57
; DEV float sigmoidf_(float x) { return __builtin_amdgcn_rcpf(1.f + __expf(-x)); }
; DEV void lora64_phase(const Params& p, int l, char* smem) {
;     ...
;     for (int mi = 0; mi < 4; ++mi) {
;       const int row = row0 + wm * 64 + mi * 16 + fr;
; #pragma unroll
;       for (int ni = 0; ni < 4; ++ni) {
;         const int c = col0 + wn * 64 + ni * 16 + fq * 4;
;         const f32x4 z = acc[mi][ni] + bv[ni];
;         uint2 o;
;         o.x = pk2(sc * sigmoidf_(z[0]), sc * sigmoidf_(z[1])); o.y = pk2(sc * sigmoidf_(z[2]), sc * sigmoidf_(z[3]));
;         *(uint2*)(O + (size_t)row * 512 + c) = o;
;       }
;     }
	v_rcp_f32_e32 v50, v49
	v_mul_f32_e32 v49, 0xbfb8aa3b, v51
	v_mul_f32_e32 v40, 0xbfb8aa3b, v40
	v_mul_f32_e32 v41, 0xbfb8aa3b, v41
	v_rcp_f32_e32 v32, v32
	v_rcp_f32_e32 v33, v33
	v_rcp_f32_e32 v28, v28
	v_rcp_f32_e32 v29, v29
	v_rcp_f32_e32 v24, v24
	v_rcp_f32_e32 v25, v25
	v_rcp_f32_e32 v102, v102
	v_rcp_f32_e32 v103, v103
	v_cvt_pk_bf16_f32 v89, v90, v91
	v_cvt_pk_bf16_f32 v90, v84, v85
	v_mul_f32_e32 v84, 0xbfb8aa3b, v86
	v_mul_f32_e32 v85, 0xbfb8aa3b, v87
	v_rcp_f32_e32 v75, v73
	v_rcp_f32_e32 v68, v68
	v_rcp_f32_e32 v69, v69
	v_exp_f32_e32 v49, v49
	v_exp_f32_e32 v40, v40
	v_exp_f32_e32 v41, v41
	v_exp_f32_e32 v84, v84
	v_exp_f32_e32 v85, v85
	v_pk_add_f32 v[100:101], v[100:101], v[166:167]
	v_pk_mul_f32 v[98:99], v[110:111], v[98:99] op_sel_hi:[0,1]
	v_pk_add_f32 v[94:95], v[94:95], v[170:171]
	v_pk_mul_f32 v[92:93], v[110:111], v[92:93] op_sel_hi:[0,1]
	v_pk_add_f32 v[82:83], v[82:83], v[166:167]
	v_pk_mul_f32 v[80:81], v[110:111], v[80:81] op_sel_hi:[0,1]
	v_pk_add_f32 v[78:79], v[78:79], v[170:171]
	v_pk_mul_f32 v[76:77], v[110:111], v[76:77] op_sel_hi:[0,1]
	v_pk_add_f32 v[66:67], v[66:67], v[166:167]
	v_pk_mul_f32 v[64:65], v[110:111], v[64:65] op_sel_hi:[0,1]
	v_pk_add_f32 v[58:59], v[58:59], v[170:171]
	v_pk_mul_f32 v[56:57], v[110:111], v[56:57] op_sel_hi:[0,1]
	v_pk_add_f32 v[34:35], v[34:35], v[166:167]
	v_pk_mul_f32 v[32:33], v[110:111], v[32:33] op_sel_hi:[0,1]
	v_pk_add_f32 v[30:31], v[30:31], v[170:171]
	v_pk_mul_f32 v[28:29], v[110:111], v[28:29] op_sel_hi:[0,1]
	v_pk_add_f32 v[26:27], v[26:27], v[174:175]
	v_pk_mul_f32 v[24:25], v[110:111], v[24:25] op_sel_hi:[0,1]
	v_lshlrev_b64 v[120:121], 10, v[112:113]
	v_pk_mul_f32 v[102:103], v[110:111], v[102:103] op_sel_hi:[0,1]
	v_cvt_pk_bf16_f32 v98, v98, v99
	v_mul_f32_e32 v99, 0xbfb8aa3b, v100
	v_cvt_pk_bf16_f32 v92, v92, v93
	v_mul_f32_e32 v93, 0xbfb8aa3b, v94
	v_cvt_pk_bf16_f32 v80, v80, v81
	v_mul_f32_e32 v81, 0xbfb8aa3b, v82
	v_cvt_pk_bf16_f32 v76, v76, v77
	v_mul_f32_e32 v77, 0xbfb8aa3b, v78
	v_pk_mul_f32 v[74:75], v[110:111], v[74:75] op_sel_hi:[0,1]
	v_pk_add_f32 v[70:71], v[70:71], v[162:163]
	v_pk_mul_f32 v[68:69], v[110:111], v[68:69] op_sel_hi:[0,1]
	v_cvt_pk_bf16_f32 v64, v64, v65
	v_mul_f32_e32 v65, 0xbfb8aa3b, v66
	v_cvt_pk_bf16_f32 v56, v56, v57
	v_mul_f32_e32 v57, 0xbfb8aa3b, v58
	v_add_f32_e32 v49, 1.0, v49
	v_add_f32_e32 v40, 1.0, v40
	v_add_f32_e32 v41, 1.0, v41
	v_cvt_pk_bf16_f32 v32, v32, v33
	v_mul_f32_e32 v33, 0xbfb8aa3b, v34
	v_cvt_pk_bf16_f32 v28, v28, v29
	v_mul_f32_e32 v29, 0xbfb8aa3b, v30
	v_cvt_pk_bf16_f32 v24, v24, v25
	v_mul_f32_e32 v25, 0xbfb8aa3b, v26
	v_lshl_add_u64 v[120:121], s[30:31], 0, v[120:121]
	v_cvt_pk_bf16_f32 v123, v102, v103
	v_lshlrev_b32_e32 v102, 1, v107
	v_mov_b32_e32 v103, v97
	v_exp_f32_e32 v99, v99
	v_exp_f32_e32 v93, v93
	v_add_f32_e32 v84, 1.0, v84
	v_add_f32_e32 v85, 1.0, v85
	v_exp_f32_e32 v81, v81
	v_exp_f32_e32 v77, v77
	v_cvt_pk_bf16_f32 v73, v74, v75
	v_cvt_pk_bf16_f32 v74, v68, v69
	v_mul_f32_e32 v68, 0xbfb8aa3b, v70
	v_mul_f32_e32 v69, 0xbfb8aa3b, v71
	v_exp_f32_e32 v65, v65
	v_exp_f32_e32 v57, v57
	v_rcp_f32_e32 v51, v49
	v_rcp_f32_e32 v40, v40
	v_rcp_f32_e32 v41, v41
	v_exp_f32_e32 v33, v33
	v_exp_f32_e32 v29, v29
	v_exp_f32_e32 v25, v25
	v_lshl_add_u64 v[104:105], v[120:121], 0, v[102:103]
	v_rcp_f32_e32 v84, v84
	v_rcp_f32_e32 v85, v85
	v_exp_f32_e32 v68, v68
	v_exp_f32_e32 v69, v69
	global_store_dwordx2 v[104:105], v[88:89], off offset:96
	v_or_b32_e32 v88, 16, v112
	v_ashrrev_i32_e32 v89, 31, v88
	v_add_f32_e32 v99, 1.0, v99
	v_add_f32_e32 v93, 1.0, v93
	v_lshlrev_b64 v[88:89], 10, v[88:89]
	v_add_f32_e32 v81, 1.0, v81
	v_add_f32_e32 v77, 1.0, v77
	v_add_f32_e32 v65, 1.0, v65
	v_add_f32_e32 v57, 1.0, v57
	v_pk_mul_f32 v[50:51], v[110:111], v[50:51] op_sel_hi:[0,1]
	v_pk_add_f32 v[42:43], v[42:43], v[162:163]
	v_pk_mul_f32 v[40:41], v[110:111], v[40:41] op_sel_hi:[0,1]
	v_add_f32_e32 v33, 1.0, v33
	v_add_f32_e32 v29, 1.0, v29
	v_add_f32_e32 v25, 1.0, v25
	v_rcp_f32_e32 v100, v99
	v_mul_f32_e32 v99, 0xbfb8aa3b, v101
	v_rcp_f32_e32 v94, v93
	v_mul_f32_e32 v93, 0xbfb8aa3b, v95
	v_lshl_add_u64 v[88:89], s[30:31], 0, v[88:89]
	v_pk_mul_f32 v[84:85], v[110:111], v[84:85] op_sel_hi:[0,1]
	v_rcp_f32_e32 v82, v81
	v_mul_f32_e32 v81, 0xbfb8aa3b, v83
	v_rcp_f32_e32 v78, v77
	v_mul_f32_e32 v77, 0xbfb8aa3b, v79
	v_add_f32_e32 v68, 1.0, v68
	v_add_f32_e32 v69, 1.0, v69
	v_rcp_f32_e32 v66, v65
	v_mul_f32_e32 v65, 0xbfb8aa3b, v67
	v_rcp_f32_e32 v58, v57
	v_mul_f32_e32 v57, 0xbfb8aa3b, v59
	v_cvt_pk_bf16_f32 v49, v50, v51
	v_cvt_pk_bf16_f32 v50, v40, v41
	v_mul_f32_e32 v40, 0xbfb8aa3b, v42
	v_mul_f32_e32 v41, 0xbfb8aa3b, v43
	v_rcp_f32_e32 v34, v33
	v_mul_f32_e32 v33, 0xbfb8aa3b, v35
	v_rcp_f32_e32 v30, v29
	v_mul_f32_e32 v29, 0xbfb8aa3b, v31
	v_rcp_f32_e32 v26, v25
	v_mul_f32_e32 v25, 0xbfb8aa3b, v27
	v_exp_f32_e32 v99, v99
	v_exp_f32_e32 v93, v93
	v_cvt_pk_bf16_f32 v91, v84, v85
	v_lshl_add_u64 v[84:85], v[88:89], 0, v[102:103]
	v_exp_f32_e32 v81, v81
	v_exp_f32_e32 v77, v77
	v_rcp_f32_e32 v68, v68
	v_rcp_f32_e32 v69, v69
	v_exp_f32_e32 v65, v65
	v_exp_f32_e32 v57, v57
; DEV float sigmoidf_(float x) { return __builtin_amdgcn_rcpf(1.f + __expf(-x)); }
; DEV int vblock() { const int per = gridDim.x >> 3; return (blockIdx.x & 7) * per + (blockIdx.x >> 3); }
; DEV void lora64_phase(const Params& p, int l, char* smem) {
;     ...
;   auto issue = [&](int L) {
;     const int job = L / 544, t = L - job * 544, pm = t >> 2, pn = t & 3;
;     const bf16_t* A = LIN + job * 64 + (size_t)(pm * 256 + lrow) * 256 + lch * 8;
;     const bf16_t* Bt = (const bf16_t*)(p.ws + O_WB + ((job & 2) ? W_LA2 : W_LW2)) + (job & 1) * 512 * 64 + (size_t)(pn * 128 + lrow) * 64 + lch * 8;
; #pragma unroll
;     for (int i = 0; i < 4; ++i) ra[i] = *(const u32x4*)(A + (size_t)(64 * i) * 256);
; #pragma unroll
;     for (int i = 0; i < 2; ++i) rb[i] = *(const u32x4*)(Bt + (size_t)(64 * i) * 64);
;   };
;   char* swa = smem + lrow * SROW + lch * 16;
;   char* swb = swa + A_ST;
;   const char* sra = smem + (wm * 64 + fr) * SROW + fq * 16;
;   const char* srb = smem + A_ST + (wn * 64 + fr) * SROW + fq * 16;
;   int L = vblock();
;   if (L < 4 * 544) issue(L);
;   for (; L < 4 * 544; L += gridDim.x) {
;     const int job = L / 544, t = L - job * 544, pm = t >> 2, pn = t & 3;
;     const int row0 = pm * 256, col0 = pn * 128;
;     __syncthreads();
; #pragma unroll
;     for (int i = 0; i < 4; ++i) *(u32x4*)(swa + i * 64 * SROW) = ra[i];
; #pragma unroll
;     for (int i = 0; i < 2; ++i) *(u32x4*)(swb + i * 64 * SROW) = rb[i];
;     __syncthreads();
;     if (L + (int)gridDim.x < 4 * 544) issue(L + gridDim.x);
;     ...
;     for (int mi = 0; mi < 4; ++mi) {
;       const int row = row0 + wm * 64 + mi * 16 + fr;
; #pragma unroll
;       for (int ni = 0; ni < 4; ++ni) {
;         const int c = col0 + wn * 64 + ni * 16 + fq * 4;
;         const f32x4 z = acc[mi][ni] + bv[ni];
;         uint2 o;
;         o.x = pk2(sc * sigmoidf_(z[0]), sc * sigmoidf_(z[1])); o.y = pk2(sc * sigmoidf_(z[2]), sc * sigmoidf_(z[3]));
;         *(uint2*)(O + (size_t)row * 512 + c) = o;
;       }
;     }
	v_exp_f32_e32 v40, v40
	v_exp_f32_e32 v41, v41
	v_exp_f32_e32 v33, v33
	v_exp_f32_e32 v29, v29
	v_exp_f32_e32 v25, v25
	global_store_dwordx2 v[84:85], v[72:73], off offset:96
	v_or_b32_e32 v72, 32, v112
	v_ashrrev_i32_e32 v73, 31, v72
	v_lshlrev_b64 v[72:73], 10, v[72:73]
	v_add_f32_e32 v99, 1.0, v99
	v_add_f32_e32 v93, 1.0, v93
	v_add_f32_e32 v81, 1.0, v81
	v_add_f32_e32 v77, 1.0, v77
	v_lshl_add_u64 v[72:73], s[30:31], 0, v[72:73]
	v_pk_mul_f32 v[68:69], v[110:111], v[68:69] op_sel_hi:[0,1]
	v_add_f32_e32 v65, 1.0, v65
	v_add_f32_e32 v57, 1.0, v57
	v_add_f32_e32 v40, 1.0, v40
	v_add_f32_e32 v41, 1.0, v41
	v_add_f32_e32 v33, 1.0, v33
	v_add_f32_e32 v29, 1.0, v29
	v_add_f32_e32 v25, 1.0, v25
	v_rcp_f32_e32 v101, v99
	v_rcp_f32_e32 v95, v93
	v_rcp_f32_e32 v83, v81
	v_rcp_f32_e32 v79, v77
	v_cvt_pk_bf16_f32 v75, v68, v69
	v_lshl_add_u64 v[68:69], v[72:73], 0, v[102:103]
	v_rcp_f32_e32 v67, v65
	v_rcp_f32_e32 v59, v57
	v_rcp_f32_e32 v40, v40
	v_rcp_f32_e32 v41, v41
	v_rcp_f32_e32 v35, v33
	v_rcp_f32_e32 v31, v29
	v_rcp_f32_e32 v27, v25
	global_store_dwordx2 v[68:69], v[48:49], off offset:96
	v_or_b32_e32 v48, 48, v112
	v_ashrrev_i32_e32 v49, 31, v48
	v_lshlrev_b64 v[48:49], 10, v[48:49]
	v_pk_mul_f32 v[100:101], v[110:111], v[100:101] op_sel_hi:[0,1]
	v_pk_mul_f32 v[94:95], v[110:111], v[94:95] op_sel_hi:[0,1]
	v_pk_mul_f32 v[82:83], v[110:111], v[82:83] op_sel_hi:[0,1]
	v_pk_mul_f32 v[78:79], v[110:111], v[78:79] op_sel_hi:[0,1]
	v_pk_mul_f32 v[66:67], v[110:111], v[66:67] op_sel_hi:[0,1]
	v_pk_mul_f32 v[58:59], v[110:111], v[58:59] op_sel_hi:[0,1]
	v_lshl_add_u64 v[48:49], s[30:31], 0, v[48:49]
	v_pk_mul_f32 v[40:41], v[110:111], v[40:41] op_sel_hi:[0,1]
	v_pk_mul_f32 v[34:35], v[110:111], v[34:35] op_sel_hi:[0,1]
	v_pk_mul_f32 v[30:31], v[110:111], v[30:31] op_sel_hi:[0,1]
	v_pk_mul_f32 v[26:27], v[110:111], v[26:27] op_sel_hi:[0,1]
	v_cvt_pk_bf16_f32 v99, v100, v101
	v_cvt_pk_bf16_f32 v93, v94, v95
	v_cvt_pk_bf16_f32 v81, v82, v83
	v_cvt_pk_bf16_f32 v77, v78, v79
	v_cvt_pk_bf16_f32 v65, v66, v67
	v_cvt_pk_bf16_f32 v57, v58, v59
	v_cvt_pk_bf16_f32 v51, v40, v41
	v_lshl_add_u64 v[40:41], v[48:49], 0, v[102:103]
	v_cvt_pk_bf16_f32 v33, v34, v35
	v_cvt_pk_bf16_f32 v29, v30, v31
	v_cvt_pk_bf16_f32 v25, v26, v27
	s_mov_b32 s30, s39
	global_store_dwordx2 v[104:105], v[122:123], off
	global_store_dwordx2 v[104:105], v[98:99], off offset:32
	global_store_dwordx2 v[104:105], v[92:93], off offset:64
	global_store_dwordx2 v[84:85], v[90:91], off
	global_store_dwordx2 v[84:85], v[80:81], off offset:32
	global_store_dwordx2 v[84:85], v[76:77], off offset:64
	global_store_dwordx2 v[68:69], v[74:75], off
	global_store_dwordx2 v[68:69], v[64:65], off offset:32
	global_store_dwordx2 v[68:69], v[56:57], off offset:64
	global_store_dwordx2 v[40:41], v[50:51], off
	global_store_dwordx2 v[40:41], v[32:33], off offset:32
	global_store_dwordx2 v[40:41], v[28:29], off offset:64
	global_store_dwordx2 v[40:41], v[24:25], off offset:96
	s_cbranch_vccz .LBB0_213
.LBB0_211:
	s_add_i32 s39, s30, s92
	s_cmpk_gt_i32 s39, 0x87f
	s_cselect_b64 s[0:1], -1, 0
	s_and_b64 vcc, exec, s[0:1]
	s_barrier
	s_waitcnt vmcnt(5)
	ds_write_b128 v116, v[0:3]
	s_waitcnt vmcnt(4)
	ds_write_b128 v116, v[4:7] offset:9216
	s_waitcnt vmcnt(3)
	ds_write_b128 v116, v[8:11] offset:18432
	s_waitcnt vmcnt(2)
	ds_write_b128 v116, v[12:15] offset:27648
	s_waitcnt vmcnt(1)
	ds_write_b128 v116, v[16:19] offset:36864
	s_waitcnt vmcnt(0)
	ds_write_b128 v116, v[20:23] offset:46080
	s_waitcnt lgkmcnt(0)
	s_barrier
	s_cbranch_vccnz .LBB0_210
	s_mul_hi_i32 s31, s39, 0x78787879
	s_lshr_b32 s40, s31, 31
	s_ashr_i32 s31, s31, 8
	s_add_i32 s31, s31, s40
	s_lshl_b32 s40, s31, 6
	s_ashr_i32 s41, s40, 31
	s_lshl_b64 s[40:41], s[40:41], 1
	v_readlane_b32 s42, v252, 3
	v_readlane_b32 s43, v252, 4
	s_add_u32 s40, s42, s40
	s_addc_u32 s41, s43, s41
	v_readlane_b32 s43, v254, 46
	s_mul_i32 s42, s31, 0xffff7800
	s_add_i32 s43, s43, s38
	s_add_i32 s43, s43, s42
	s_and_b32 s42, s43, 0xffffff00
	v_add_u32_e32 v0, s42, v111
	v_ashrrev_i32_e32 v1, 31, v0
	v_lshlrev_b64 v[0:1], 9, v[0:1]
	v_lshl_add_u64 v[0:1], s[40:41], 0, v[0:1]
	s_bitcmp0_b32 s31, 1
	s_mov_b32 s40, 0x2400000
	s_cselect_b32 s40, s40, 0x2420000
	s_add_u32 s40, s48, s40
	s_addc_u32 s41, s49, 0
	s_lshl_b32 s31, s31, 16
	s_and_b32 s31, s31, 0x10000
	v_mov_b32_e32 v107, v97
	s_add_u32 s40, s40, s31
	v_readlane_b32 s31, v254, 48
	v_lshl_add_u64 v[8:9], v[0:1], 0, v[106:107]
	s_addc_u32 s41, s41, 0
	s_add_i32 s31, s31, s37
	s_and_b32 s31, s31, 0x180
	v_add_co_u32_e32 v4, vcc, 0x8000, v8
	v_add_u32_e32 v0, s31, v111
	s_nop 0
	v_addc_co_u32_e32 v5, vcc, 0, v9, vcc
	v_ashrrev_i32_e32 v1, 31, v0
	v_add_co_u32_e32 v10, vcc, 0x10000, v8
	v_lshlrev_b64 v[0:1], 7, v[0:1]
	s_nop 0
	v_addc_co_u32_e32 v11, vcc, 0, v9, vcc
	v_lshl_add_u64 v[16:17], s[40:41], 0, v[0:1]
	v_add_co_u32_e32 v12, vcc, 0x18000, v8
	v_lshl_add_u64 v[16:17], v[16:17], 0, v[106:107]
	s_nop 0
	v_addc_co_u32_e32 v13, vcc, 0, v9, vcc
	v_add_co_u32_e32 v20, vcc, 0x2000, v16
	s_nop 1
	v_addc_co_u32_e32 v21, vcc, 0, v17, vcc
	s_nop 0
	s_nop 0
	s_nop 0
	s_branch .LBB0_210

; DEV void cvt_job(const float* __restrict__ src, int K, int N, int ldsrc, bf16_t* __restrict__ dst, int nperm, int& tbase, char* smem) {
;     ...
;   for (int t = first; t < cnt; t += G) {
;     const int kt = t % nkt, nt = t / nkt;
;     const int ty = tid >> 4, tx = tid & 15;
;     const int n = nt * 64 + tx * 4;
;     const int sc = (n < nperm) ? conv_srccol(n) : n;
; #pragma unroll
;     for (int i = 0; i < 2; ++i) {
;       const int k = ty + 32 * i;
;       const float4 v = *(const float4*)(src + (size_t)(kt * 64 + k) * ldsrc + sc);
;       float* d = lds + k * 65 + tx * 4;
;       d[0] = v.x; d[1] = v.y; d[2] = v.z; d[3] = v.w;
;     }
;     __syncthreads();
;     {
;       const int nn = tid >> 3, kc = tid & 7;
;       float v[8];
; #pragma unroll
;       for (int j = 0; j < 8; ++j) v[j] = lds[(kc * 8 + j) * 65 + nn];
;       uint4 o;
;       o.x = pk2(v[0], v[1]); o.y = pk2(v[2], v[3]); o.z = pk2(v[4], v[5]); o.w = pk2(v[6], v[7]);
;       *(uint4*)(dst + (size_t)(nt * 64 + nn) * K + kt * 64 + kc * 8) = o;
;     }
;     __syncthreads();
;   }
.LBB0_230:
	s_or_b64 exec, exec, s[0:1]
	s_mul_i32 s100, s92, 3
	s_add_i32 s100, s100, s31
	s_cmpk_lt_i32 s100, 0x460
	s_cselect_b32 s100, 0x3000, 0
	s_mov_b32 s101, 0
	s_lshl_b32 s0, s37, 10
	v_readlane_b32 s76, v254, 58
	s_sub_i32 s0, s30, s0
	v_ashrrev_i32_e32 v1, 31, v0
	v_readlane_b32 s77, v254, 59
	v_add_u32_e32 v7, s0, v2
	v_add_u32_e32 v16, 0x2088, v5
	v_lshl_add_u64 v[0:1], v[0:1], 2, s[76:77]
	v_mad_i64_i32 v[8:9], s[38:39], v7, s29, v[0:1]
	v_lshl_add_u64 v[242:243], v[8:9], 0, s[100:101]
	global_load_dwordx4 v[8:11], v[8:9], off
	v_add_u32_e32 v7, 32, v7
	v_mad_i64_i32 v[0:1], s[38:39], v7, s29, v[0:1]
	v_lshl_add_u64 v[244:245], v[0:1], 0, s[100:101]
	global_load_dwordx4 v[12:15], v[0:1], off
	global_load_dword v238, v[242:243], off
	global_load_dword v239, v[244:245], off
	v_add_u32_e32 v7, 0x2080, v5
	v_add_u32_e32 v17, 0x400, v6
	v_add_u32_e32 v0, s36, v4
	v_ashrrev_i32_e32 v1, 31, v0
	v_lshlrev_b64 v[0:1], 11, v[0:1]
	s_ashr_i32 s1, s0, 31
	v_lshl_add_u64 v[0:1], s[62:63], 0, v[0:1]
	s_add_i32 s31, s31, s92
	s_add_i32 s30, s30, s33
	v_lshl_add_u64 v[0:1], s[0:1], 1, v[0:1]
	s_cmpk_lt_i32 s31, 0x460
	v_lshl_add_u64 v[0:1], v[0:1], 0, v[96:97]
	v_readlane_b32 s78, v254, 60
	v_readlane_b32 s79, v254, 61
	v_readlane_b32 s80, v254, 62
	v_readlane_b32 s81, v254, 63
	v_readlane_b32 s82, v255, 0
	v_readlane_b32 s83, v255, 1
	v_readlane_b32 s84, v255, 2
	v_readlane_b32 s85, v255, 3
	v_readlane_b32 s86, v255, 4
	v_readlane_b32 s87, v255, 5
	v_readlane_b32 s88, v255, 6
	v_readlane_b32 s89, v255, 7
	v_readlane_b32 s90, v255, 8
	v_readlane_b32 s91, v255, 9
	s_waitcnt vmcnt(3)
	ds_write2_b32 v5, v8, v9 offset1:1
	ds_write2_b32 v5, v10, v11 offset0:2 offset1:3
	s_waitcnt vmcnt(2)
	ds_write2_b32 v7, v12, v13 offset1:1
	ds_write2_b32 v16, v14, v15 offset1:1
	s_waitcnt lgkmcnt(0)
	s_barrier
	ds_read2_b32 v[8:9], v6 offset1:65
	ds_read2_b32 v[10:11], v6 offset0:130 offset1:195
	ds_read2_b32 v[12:13], v17 offset0:4 offset1:69
	ds_read2_b32 v[14:15], v17 offset0:134 offset1:199
	s_waitcnt lgkmcnt(3)
	v_cvt_pk_bf16_f32 v8, v8, v9
	s_waitcnt lgkmcnt(2)
	v_cvt_pk_bf16_f32 v9, v10, v11
	s_waitcnt lgkmcnt(1)
	v_cvt_pk_bf16_f32 v10, v12, v13
	s_waitcnt lgkmcnt(0)
	v_cvt_pk_bf16_f32 v11, v14, v15
	global_store_dwordx4 v[0:1], v[8:11], off
	s_barrier
	s_cbranch_scc0 .LBB0_233

; DEV void cvt_job(const float* __restrict__ src, int K, int N, int ldsrc, bf16_t* __restrict__ dst, int nperm, int& tbase, char* smem) {
;     ...
;   for (int t = first; t < cnt; t += G) {
;     const int kt = t % nkt, nt = t / nkt;
;     const int ty = tid >> 4, tx = tid & 15;
;     const int n = nt * 64 + tx * 4;
;     const int sc = (n < nperm) ? conv_srccol(n) : n;
; #pragma unroll
;     for (int i = 0; i < 2; ++i) {
;       const int k = ty + 32 * i;
;       const float4 v = *(const float4*)(src + (size_t)(kt * 64 + k) * ldsrc + sc);
;       float* d = lds + k * 65 + tx * 4;
;       d[0] = v.x; d[1] = v.y; d[2] = v.z; d[3] = v.w;
;     }
;     __syncthreads();
;     {
;       const int nn = tid >> 3, kc = tid & 7;
;       float v[8];
; #pragma unroll
;       for (int j = 0; j < 8; ++j) v[j] = lds[(kc * 8 + j) * 65 + nn];
;       uint4 o;
;       o.x = pk2(v[0], v[1]); o.y = pk2(v[2], v[3]); o.z = pk2(v[4], v[5]); o.w = pk2(v[6], v[7]);
;       *(uint4*)(dst + (size_t)(nt * 64 + nn) * K + kt * 64 + kc * 8) = o;
;     }
;     __syncthreads();
;   }
.LBB0_235:
	s_mul_i32 s100, s92, 3
	s_add_i32 s100, s100, s1
	s_cmpk_lt_i32 s100, 0x300
	s_cselect_b32 s100, 0x3000, 0
	s_mov_b32 s101, 0
	s_lshl_b32 s31, s31, 10
	v_readlane_b32 s38, v251, 3
	s_sub_i32 s36, s0, s31
	v_ashrrev_i32_e32 v1, 31, v0
	v_readlane_b32 s39, v251, 4
	v_add_u32_e32 v7, s36, v2
	v_add_u32_e32 v16, 0x2088, v5
	v_lshl_add_u64 v[0:1], v[0:1], 2, s[38:39]
	v_mad_i64_i32 v[8:9], s[38:39], v7, s29, v[0:1]
	v_lshl_add_u64 v[242:243], v[8:9], 0, s[100:101]
	global_load_dwordx4 v[8:11], v[8:9], off
	v_add_u32_e32 v7, 32, v7
	v_mad_i64_i32 v[0:1], s[38:39], v7, s29, v[0:1]
	v_lshl_add_u64 v[244:245], v[0:1], 0, s[100:101]
	global_load_dwordx4 v[12:15], v[0:1], off
	global_load_dword v238, v[242:243], off
	global_load_dword v239, v[244:245], off
	v_add_u32_e32 v7, 0x2080, v5
	v_add_u32_e32 v17, 0x400, v6
	v_add_u32_e32 v0, s30, v4
	v_ashrrev_i32_e32 v1, 31, v0
	v_readlane_b32 s30, v251, 5
	v_lshlrev_b64 v[0:1], 11, v[0:1]
	v_readlane_b32 s31, v251, 6
	s_ashr_i32 s37, s36, 31
	s_add_i32 s1, s1, s92
	v_lshl_add_u64 v[0:1], s[30:31], 0, v[0:1]
	s_add_i32 s0, s0, s33
	v_lshl_add_u64 v[0:1], s[36:37], 1, v[0:1]
	s_cmpk_lt_i32 s1, 0x300
	v_lshl_add_u64 v[0:1], v[0:1], 0, v[96:97]
	s_waitcnt vmcnt(3)
	ds_write2_b32 v5, v8, v9 offset1:1
	ds_write2_b32 v5, v10, v11 offset0:2 offset1:3
	s_waitcnt vmcnt(2)
	ds_write2_b32 v7, v12, v13 offset1:1
	ds_write2_b32 v16, v14, v15 offset1:1
	s_waitcnt lgkmcnt(0)
	s_barrier
	ds_read2_b32 v[8:9], v6 offset1:65
	ds_read2_b32 v[10:11], v6 offset0:130 offset1:195
	ds_read2_b32 v[12:13], v17 offset0:4 offset1:69
	ds_read2_b32 v[14:15], v17 offset0:134 offset1:199
	s_waitcnt lgkmcnt(3)
	v_cvt_pk_bf16_f32 v8, v8, v9
	s_waitcnt lgkmcnt(2)
	v_cvt_pk_bf16_f32 v9, v10, v11
	s_waitcnt lgkmcnt(1)
	v_cvt_pk_bf16_f32 v10, v12, v13
	s_waitcnt lgkmcnt(0)
	v_cvt_pk_bf16_f32 v11, v14, v15
	global_store_dwordx4 v[0:1], v[8:11], off
	s_barrier
	s_cbranch_scc0 .LBB0_238

; DEV void cvt_job(const float* __restrict__ src, int K, int N, int ldsrc, bf16_t* __restrict__ dst, int nperm, int& tbase, char* smem) {
;     ...
;   for (int t = first; t < cnt; t += G) {
;     const int kt = t % nkt, nt = t / nkt;
;     const int ty = tid >> 4, tx = tid & 15;
;     const int n = nt * 64 + tx * 4;
;     const int sc = (n < nperm) ? conv_srccol(n) : n;
; #pragma unroll
;     for (int i = 0; i < 2; ++i) {
;       const int k = ty + 32 * i;
;       const float4 v = *(const float4*)(src + (size_t)(kt * 64 + k) * ldsrc + sc);
;       float* d = lds + k * 65 + tx * 4;
;       d[0] = v.x; d[1] = v.y; d[2] = v.z; d[3] = v.w;
;     }
;     __syncthreads();
;     {
;       const int nn = tid >> 3, kc = tid & 7;
;       float v[8];
; #pragma unroll
;       for (int j = 0; j < 8; ++j) v[j] = lds[(kc * 8 + j) * 65 + nn];
;       uint4 o;
;       o.x = pk2(v[0], v[1]); o.y = pk2(v[2], v[3]); o.z = pk2(v[4], v[5]); o.w = pk2(v[6], v[7]);
;       *(uint4*)(dst + (size_t)(nt * 64 + nn) * K + kt * 64 + kc * 8) = o;
;     }
;     __syncthreads();
;   }
.LBB0_240:
	s_mul_i32 s100, s92, 3
	s_add_i32 s100, s100, s1
	s_cmpk_lt_i32 s100, 0x400
	s_cselect_b32 s100, 0x3000, 0
	s_mov_b32 s101, 0
	s_lshl_b32 s31, s31, 10
	s_sub_i32 s36, s0, s31
	v_add_u32_e32 v12, s36, v2
	v_ashrrev_i32_e32 v1, 31, v0
	v_ashrrev_i32_e32 v13, 31, v12
	v_lshl_add_u64 v[0:1], v[0:1], 2, s[22:23]
	v_lshlrev_b64 v[8:9], 14, v[12:13]
	v_add_u32_e32 v12, 32, v12
	v_lshl_add_u64 v[8:9], v[0:1], 0, v[8:9]
	v_ashrrev_i32_e32 v13, 31, v12
	v_lshl_add_u64 v[242:243], v[8:9], 0, s[100:101]
	global_load_dwordx4 v[8:11], v[8:9], off
	v_lshlrev_b64 v[12:13], 14, v[12:13]
	v_lshl_add_u64 v[0:1], v[0:1], 0, v[12:13]
	v_lshl_add_u64 v[244:245], v[0:1], 0, s[100:101]
	global_load_dwordx4 v[12:15], v[0:1], off
	global_load_dword v238, v[242:243], off
	global_load_dword v239, v[244:245], off
	v_add_u32_e32 v7, 0x2080, v5
	v_add_u32_e32 v16, 0x2088, v5
	v_add_u32_e32 v17, 0x400, v6
	v_add_u32_e32 v0, s30, v4
	v_ashrrev_i32_e32 v1, 31, v0
	v_readlane_b32 s30, v251, 7
	v_lshlrev_b64 v[0:1], 11, v[0:1]
	v_readlane_b32 s31, v251, 8
	s_ashr_i32 s37, s36, 31
	s_add_i32 s1, s1, s92
	v_lshl_add_u64 v[0:1], s[30:31], 0, v[0:1]
	s_add_i32 s0, s0, s33
	v_lshl_add_u64 v[0:1], s[36:37], 1, v[0:1]
	s_cmpk_lt_i32 s1, 0x400
	v_lshl_add_u64 v[0:1], v[0:1], 0, v[96:97]
	s_waitcnt vmcnt(3)
	ds_write2_b32 v5, v8, v9 offset1:1
	ds_write2_b32 v5, v10, v11 offset0:2 offset1:3
	s_waitcnt vmcnt(2)
	ds_write2_b32 v7, v12, v13 offset1:1
	ds_write2_b32 v16, v14, v15 offset1:1
	s_waitcnt lgkmcnt(0)
	s_barrier
	ds_read2_b32 v[8:9], v6 offset1:65
	ds_read2_b32 v[10:11], v6 offset0:130 offset1:195
	ds_read2_b32 v[12:13], v17 offset0:4 offset1:69
	ds_read2_b32 v[14:15], v17 offset0:134 offset1:199
	s_waitcnt lgkmcnt(3)
	v_cvt_pk_bf16_f32 v8, v8, v9
	s_waitcnt lgkmcnt(2)
	v_cvt_pk_bf16_f32 v9, v10, v11
	s_waitcnt lgkmcnt(1)
	v_cvt_pk_bf16_f32 v10, v12, v13
	s_waitcnt lgkmcnt(0)
	v_cvt_pk_bf16_f32 v11, v14, v15
	global_store_dwordx4 v[0:1], v[8:11], off
	s_barrier
	s_cbranch_scc0 .LBB0_243

; DEV void cvt_job(const float* __restrict__ src, int K, int N, int ldsrc, bf16_t* __restrict__ dst, int nperm, int& tbase, char* smem) {
;     ...
;   for (int t = first; t < cnt; t += G) {
;     const int kt = t % nkt, nt = t / nkt;
;     const int ty = tid >> 4, tx = tid & 15;
;     const int n = nt * 64 + tx * 4;
;     const int sc = (n < nperm) ? conv_srccol(n) : n;
; #pragma unroll
;     for (int i = 0; i < 2; ++i) {
;       const int k = ty + 32 * i;
;       const float4 v = *(const float4*)(src + (size_t)(kt * 64 + k) * ldsrc + sc);
;       float* d = lds + k * 65 + tx * 4;
;       d[0] = v.x; d[1] = v.y; d[2] = v.z; d[3] = v.w;
;     }
;     __syncthreads();
;     {
;       const int nn = tid >> 3, kc = tid & 7;
;       float v[8];
; #pragma unroll
;       for (int j = 0; j < 8; ++j) v[j] = lds[(kc * 8 + j) * 65 + nn];
;       uint4 o;
;       o.x = pk2(v[0], v[1]); o.y = pk2(v[2], v[3]); o.z = pk2(v[4], v[5]); o.w = pk2(v[6], v[7]);
;       *(uint4*)(dst + (size_t)(nt * 64 + nn) * K + kt * 64 + kc * 8) = o;
;     }
;     __syncthreads();
;   }
.LBB0_245:
	s_mul_i32 s100, s92, 3
	s_add_i32 s100, s100, s1
	s_cmpk_lt_i32 s100, 0x400
	s_cselect_b32 s100, 0xc00, 0
	s_mov_b32 s101, 0
	s_lshl_b32 s31, s31, 12
	s_sub_i32 s36, s0, s31
	v_add_u32_e32 v12, s36, v2
	v_ashrrev_i32_e32 v1, 31, v0
	v_ashrrev_i32_e32 v13, 31, v12
	v_lshl_add_u64 v[0:1], v[0:1], 2, s[24:25]
	v_lshlrev_b64 v[8:9], 12, v[12:13]
	v_add_u32_e32 v12, 32, v12
	v_lshl_add_u64 v[8:9], v[0:1], 0, v[8:9]
	v_ashrrev_i32_e32 v13, 31, v12
	v_lshl_add_u64 v[242:243], v[8:9], 0, s[100:101]
	global_load_dwordx4 v[8:11], v[8:9], off
	v_lshlrev_b64 v[12:13], 12, v[12:13]
	v_lshl_add_u64 v[0:1], v[0:1], 0, v[12:13]
	v_lshl_add_u64 v[244:245], v[0:1], 0, s[100:101]
	global_load_dwordx4 v[12:15], v[0:1], off
	global_load_dword v238, v[242:243], off
	global_load_dword v239, v[244:245], off
	v_add_u32_e32 v7, 0x2080, v5
	v_add_u32_e32 v16, 0x2088, v5
	v_add_u32_e32 v17, 0x400, v6
	v_add_u32_e32 v0, s30, v4
	v_ashrrev_i32_e32 v1, 31, v0
	v_readlane_b32 s30, v251, 9
	v_lshlrev_b64 v[0:1], 13, v[0:1]
	v_readlane_b32 s31, v251, 10
	s_ashr_i32 s37, s36, 31
	s_add_i32 s1, s1, s92
	v_lshl_add_u64 v[0:1], s[30:31], 0, v[0:1]
	s_add_i32 s0, s0, s33
	v_lshl_add_u64 v[0:1], s[36:37], 1, v[0:1]
	s_cmpk_lt_i32 s1, 0x400
	v_lshl_add_u64 v[0:1], v[0:1], 0, v[96:97]
	s_waitcnt vmcnt(3)
	ds_write2_b32 v5, v8, v9 offset1:1
	ds_write2_b32 v5, v10, v11 offset0:2 offset1:3
	s_waitcnt vmcnt(2)
	ds_write2_b32 v7, v12, v13 offset1:1
	ds_write2_b32 v16, v14, v15 offset1:1
	s_waitcnt lgkmcnt(0)
	s_barrier
	ds_read2_b32 v[8:9], v6 offset1:65
	ds_read2_b32 v[10:11], v6 offset0:130 offset1:195
	ds_read2_b32 v[12:13], v17 offset0:4 offset1:69
	ds_read2_b32 v[14:15], v17 offset0:134 offset1:199
	s_waitcnt lgkmcnt(3)
	v_cvt_pk_bf16_f32 v8, v8, v9
	s_waitcnt lgkmcnt(2)
	v_cvt_pk_bf16_f32 v9, v10, v11
	s_waitcnt lgkmcnt(1)
	v_cvt_pk_bf16_f32 v10, v12, v13
	s_waitcnt lgkmcnt(0)
	v_cvt_pk_bf16_f32 v11, v14, v15
	global_store_dwordx4 v[0:1], v[8:11], off
	s_barrier
	s_cbranch_scc0 .LBB0_248

; DEV void cvt_job(const float* __restrict__ src, int K, int N, int ldsrc, bf16_t* __restrict__ dst, int nperm, int& tbase, char* smem) {
;     ...
;   for (int t = first; t < cnt; t += G) {
;     const int kt = t % nkt, nt = t / nkt;
;     const int ty = tid >> 4, tx = tid & 15;
;     const int n = nt * 64 + tx * 4;
;     const int sc = (n < nperm) ? conv_srccol(n) : n;
; #pragma unroll
;     for (int i = 0; i < 2; ++i) {
;       const int k = ty + 32 * i;
;       const float4 v = *(const float4*)(src + (size_t)(kt * 64 + k) * ldsrc + sc);
;       float* d = lds + k * 65 + tx * 4;
;       d[0] = v.x; d[1] = v.y; d[2] = v.z; d[3] = v.w;
;     }
;     __syncthreads();
;     {
;       const int nn = tid >> 3, kc = tid & 7;
;       float v[8];
; #pragma unroll
;       for (int j = 0; j < 8; ++j) v[j] = lds[(kc * 8 + j) * 65 + nn];
;       uint4 o;
;       o.x = pk2(v[0], v[1]); o.y = pk2(v[2], v[3]); o.z = pk2(v[4], v[5]); o.w = pk2(v[6], v[7]);
;       *(uint4*)(dst + (size_t)(nt * 64 + nn) * K + kt * 64 + kc * 8) = o;
;     }
;     __syncthreads();
;   }
.LBB0_250:
	s_mul_i32 s100, s92, 3
	s_add_i32 s100, s100, s1
	s_cmpk_lt_i32 s100, 0x100
	s_cselect_b32 s100, 0x3000, 0
	s_mov_b32 s101, 0
	s_lshl_b32 s31, s31, 10
	s_sub_i32 s36, s0, s31
	v_add_u32_e32 v12, s36, v2
	v_ashrrev_i32_e32 v1, 31, v0
	v_ashrrev_i32_e32 v13, 31, v12
	v_lshl_add_u64 v[0:1], v[0:1], 2, s[20:21]
	v_lshlrev_b64 v[8:9], 12, v[12:13]
	v_add_u32_e32 v12, 32, v12
	v_lshl_add_u64 v[8:9], v[0:1], 0, v[8:9]
	v_ashrrev_i32_e32 v13, 31, v12
	v_lshl_add_u64 v[242:243], v[8:9], 0, s[100:101]
	global_load_dwordx4 v[8:11], v[8:9], off
	v_lshlrev_b64 v[12:13], 12, v[12:13]
	v_lshl_add_u64 v[0:1], v[0:1], 0, v[12:13]
	v_lshl_add_u64 v[244:245], v[0:1], 0, s[100:101]
	global_load_dwordx4 v[12:15], v[0:1], off
	global_load_dword v238, v[242:243], off
	global_load_dword v239, v[244:245], off
	v_add_u32_e32 v7, 0x2080, v5
	v_add_u32_e32 v16, 0x2088, v5
	v_add_u32_e32 v17, 0x400, v6
	v_add_u32_e32 v0, s30, v4
	v_ashrrev_i32_e32 v1, 31, v0
	v_readlane_b32 s30, v251, 11
	v_lshlrev_b64 v[0:1], 11, v[0:1]
	v_readlane_b32 s31, v251, 12
	s_ashr_i32 s37, s36, 31
	s_add_i32 s1, s1, s92
	v_lshl_add_u64 v[0:1], s[30:31], 0, v[0:1]
	s_add_i32 s0, s0, s33
	v_lshl_add_u64 v[0:1], s[36:37], 1, v[0:1]
	s_cmpk_lt_i32 s1, 0x100
	v_lshl_add_u64 v[0:1], v[0:1], 0, v[96:97]
	s_waitcnt vmcnt(3)
	ds_write2_b32 v5, v8, v9 offset1:1
	ds_write2_b32 v5, v10, v11 offset0:2 offset1:3
	s_waitcnt vmcnt(2)
	ds_write2_b32 v7, v12, v13 offset1:1
	ds_write2_b32 v16, v14, v15 offset1:1
	s_waitcnt lgkmcnt(0)
	s_barrier
	ds_read2_b32 v[8:9], v6 offset1:65
	ds_read2_b32 v[10:11], v6 offset0:130 offset1:195
	ds_read2_b32 v[12:13], v17 offset0:4 offset1:69
	ds_read2_b32 v[14:15], v17 offset0:134 offset1:199
	s_waitcnt lgkmcnt(3)
	v_cvt_pk_bf16_f32 v8, v8, v9
	s_waitcnt lgkmcnt(2)
	v_cvt_pk_bf16_f32 v9, v10, v11
	s_waitcnt lgkmcnt(1)
	v_cvt_pk_bf16_f32 v10, v12, v13
	s_waitcnt lgkmcnt(0)
	v_cvt_pk_bf16_f32 v11, v14, v15
	global_store_dwordx4 v[0:1], v[8:11], off
	s_barrier
	s_cbranch_scc0 .LBB0_253

; DEV void cvt_job(const float* __restrict__ src, int K, int N, int ldsrc, bf16_t* __restrict__ dst, int nperm, int& tbase, char* smem) {
;     ...
;   for (int t = first; t < cnt; t += G) {
;     const int kt = t % nkt, nt = t / nkt;
;     const int ty = tid >> 4, tx = tid & 15;
;     const int n = nt * 64 + tx * 4;
;     const int sc = (n < nperm) ? conv_srccol(n) : n;
; #pragma unroll
;     for (int i = 0; i < 2; ++i) {
;       const int k = ty + 32 * i;
;       const float4 v = *(const float4*)(src + (size_t)(kt * 64 + k) * ldsrc + sc);
;       float* d = lds + k * 65 + tx * 4;
;       d[0] = v.x; d[1] = v.y; d[2] = v.z; d[3] = v.w;
;     }
;     __syncthreads();
;     {
;       const int nn = tid >> 3, kc = tid & 7;
;       float v[8];
; #pragma unroll
;       for (int j = 0; j < 8; ++j) v[j] = lds[(kc * 8 + j) * 65 + nn];
;       uint4 o;
;       o.x = pk2(v[0], v[1]); o.y = pk2(v[2], v[3]); o.z = pk2(v[4], v[5]); o.w = pk2(v[6], v[7]);
;       *(uint4*)(dst + (size_t)(nt * 64 + nn) * K + kt * 64 + kc * 8) = o;
;     }
;     __syncthreads();
;   }
.LBB0_255:
	s_mul_i32 s100, s92, 3
	s_add_i32 s100, s100, s1
	s_cmpk_lt_i32 s100, 0x80
	s_cselect_b32 s100, 0x6000, 0
	s_mov_b32 s101, 0
	s_lshl_b32 s31, s31, 9
	s_sub_i32 s36, s0, s31
	v_readlane_b32 s76, v254, 58
	v_add_u32_e32 v12, s36, v2
	v_ashrrev_i32_e32 v1, 31, v0
	v_readlane_b32 s86, v255, 4
	v_readlane_b32 s87, v255, 5
	v_ashrrev_i32_e32 v13, 31, v12
	v_lshlrev_b64 v[8:9], 12, v[12:13]
	v_lshl_add_u64 v[0:1], v[0:1], 2, s[86:87]
	v_add_u32_e32 v12, 32, v12
	v_lshl_add_u64 v[8:9], v[0:1], 0, v[8:9]
	v_ashrrev_i32_e32 v13, 31, v12
	v_lshl_add_u64 v[242:243], v[8:9], 0, s[100:101]
	global_load_dwordx4 v[8:11], v[8:9], off
	v_lshlrev_b64 v[12:13], 12, v[12:13]
	v_lshl_add_u64 v[0:1], v[0:1], 0, v[12:13]
	v_lshl_add_u64 v[244:245], v[0:1], 0, s[100:101]
	global_load_dwordx4 v[12:15], v[0:1], off
	global_load_dword v238, v[242:243], off
	global_load_dword v239, v[244:245], off
	v_add_u32_e32 v7, 0x2080, v5
	v_add_u32_e32 v16, 0x2088, v5
	v_add_u32_e32 v17, 0x400, v6
	v_add_u32_e32 v0, s30, v4
	v_ashrrev_i32_e32 v1, 31, v0
	v_readlane_b32 s30, v251, 13
	v_lshlrev_b64 v[0:1], 10, v[0:1]
	v_readlane_b32 s31, v251, 14
	s_ashr_i32 s37, s36, 31
	s_add_i32 s1, s1, s92
	v_lshl_add_u64 v[0:1], s[30:31], 0, v[0:1]
	s_add_i32 s0, s0, s33
	v_lshl_add_u64 v[0:1], s[36:37], 1, v[0:1]
	s_cmpk_lt_i32 s1, 0x80
	v_lshl_add_u64 v[0:1], v[0:1], 0, v[96:97]
	v_readlane_b32 s77, v254, 59
	v_readlane_b32 s78, v254, 60
	v_readlane_b32 s79, v254, 61
	v_readlane_b32 s80, v254, 62
	v_readlane_b32 s81, v254, 63
	v_readlane_b32 s82, v255, 0
	v_readlane_b32 s83, v255, 1
	v_readlane_b32 s84, v255, 2
	v_readlane_b32 s85, v255, 3
	v_readlane_b32 s88, v255, 6
	v_readlane_b32 s89, v255, 7
	v_readlane_b32 s90, v255, 8
	v_readlane_b32 s91, v255, 9
	s_waitcnt vmcnt(3)
	ds_write2_b32 v5, v8, v9 offset1:1
	ds_write2_b32 v5, v10, v11 offset0:2 offset1:3
	s_waitcnt vmcnt(2)
	ds_write2_b32 v7, v12, v13 offset1:1
	ds_write2_b32 v16, v14, v15 offset1:1
	s_waitcnt lgkmcnt(0)
	s_barrier
	ds_read2_b32 v[8:9], v6 offset1:65
	ds_read2_b32 v[10:11], v6 offset0:130 offset1:195
	ds_read2_b32 v[12:13], v17 offset0:4 offset1:69
	ds_read2_b32 v[14:15], v17 offset0:134 offset1:199
	s_waitcnt lgkmcnt(3)
	v_cvt_pk_bf16_f32 v8, v8, v9
	s_waitcnt lgkmcnt(2)
	v_cvt_pk_bf16_f32 v9, v10, v11
	s_waitcnt lgkmcnt(1)
	v_cvt_pk_bf16_f32 v10, v12, v13
	s_waitcnt lgkmcnt(0)
	v_cvt_pk_bf16_f32 v11, v14, v15
	global_store_dwordx4 v[0:1], v[8:11], off
	s_barrier
	s_cbranch_scc0 .LBB0_258

; DEV void cvt_job(const float* __restrict__ src, int K, int N, int ldsrc, bf16_t* __restrict__ dst, int nperm, int& tbase, char* smem) {
;     ...
;   for (int t = first; t < cnt; t += G) {
;     const int kt = t % nkt, nt = t / nkt;
;     const int ty = tid >> 4, tx = tid & 15;
;     const int n = nt * 64 + tx * 4;
;     const int sc = (n < nperm) ? conv_srccol(n) : n;
; #pragma unroll
;     for (int i = 0; i < 2; ++i) {
;       const int k = ty + 32 * i;
;       const float4 v = *(const float4*)(src + (size_t)(kt * 64 + k) * ldsrc + sc);
;       float* d = lds + k * 65 + tx * 4;
;       d[0] = v.x; d[1] = v.y; d[2] = v.z; d[3] = v.w;
;     }
;     __syncthreads();
;     {
;       const int nn = tid >> 3, kc = tid & 7;
;       float v[8];
; #pragma unroll
;       for (int j = 0; j < 8; ++j) v[j] = lds[(kc * 8 + j) * 65 + nn];
;       uint4 o;
;       o.x = pk2(v[0], v[1]); o.y = pk2(v[2], v[3]); o.z = pk2(v[4], v[5]); o.w = pk2(v[6], v[7]);
;       *(uint4*)(dst + (size_t)(nt * 64 + nn) * K + kt * 64 + kc * 8) = o;
;     }
;     __syncthreads();
;   }
.LBB0_260:
	s_mul_i32 s100, s92, 3
	s_add_i32 s100, s100, s1
	s_cmpk_lt_i32 s100, 0x80
	s_cselect_b32 s100, 0x6000, 0
	s_mov_b32 s101, 0
	s_lshl_b32 s31, s31, 9
	s_sub_i32 s36, s0, s31
	v_readlane_b32 s76, v251, 21
	v_add_u32_e32 v12, s36, v2
	v_ashrrev_i32_e32 v1, 31, v0
	v_readlane_b32 s82, v251, 27
	v_readlane_b32 s83, v251, 28
	v_ashrrev_i32_e32 v13, 31, v12
	v_lshlrev_b64 v[8:9], 12, v[12:13]
	v_lshl_add_u64 v[0:1], v[0:1], 2, s[82:83]
	v_add_u32_e32 v12, 32, v12
	v_lshl_add_u64 v[8:9], v[0:1], 0, v[8:9]
	v_ashrrev_i32_e32 v13, 31, v12
	v_lshl_add_u64 v[242:243], v[8:9], 0, s[100:101]
	global_load_dwordx4 v[8:11], v[8:9], off
	v_lshlrev_b64 v[12:13], 12, v[12:13]
	v_lshl_add_u64 v[0:1], v[0:1], 0, v[12:13]
	v_lshl_add_u64 v[244:245], v[0:1], 0, s[100:101]
	global_load_dwordx4 v[12:15], v[0:1], off
	global_load_dword v238, v[242:243], off
	global_load_dword v239, v[244:245], off
	v_add_u32_e32 v7, 0x2080, v5
	v_add_u32_e32 v16, 0x2088, v5
	v_add_u32_e32 v17, 0x400, v6
	v_add_u32_e32 v0, s30, v4
	v_ashrrev_i32_e32 v1, 31, v0
	v_lshlrev_b64 v[0:1], 10, v[0:1]
	s_ashr_i32 s37, s36, 31
	v_lshl_add_u64 v[0:1], s[66:67], 0, v[0:1]
	s_add_i32 s1, s1, s92
	s_add_i32 s0, s0, s33
	v_lshl_add_u64 v[0:1], s[36:37], 1, v[0:1]
	s_cmpk_lt_i32 s1, 0x80
	v_lshl_add_u64 v[0:1], v[0:1], 0, v[96:97]
	v_readlane_b32 s77, v251, 22
	v_readlane_b32 s78, v251, 23
	v_readlane_b32 s79, v251, 24
	v_readlane_b32 s80, v251, 25
	v_readlane_b32 s81, v251, 26
	v_readlane_b32 s84, v251, 29
	v_readlane_b32 s85, v251, 30
	v_readlane_b32 s86, v251, 31
	v_readlane_b32 s87, v251, 32
	v_readlane_b32 s88, v251, 33
	v_readlane_b32 s89, v251, 34
	v_readlane_b32 s90, v251, 35
	v_readlane_b32 s91, v251, 36
	s_waitcnt vmcnt(3)
	ds_write2_b32 v5, v8, v9 offset1:1
	ds_write2_b32 v5, v10, v11 offset0:2 offset1:3
	s_waitcnt vmcnt(2)
	ds_write2_b32 v7, v12, v13 offset1:1
	ds_write2_b32 v16, v14, v15 offset1:1
	s_waitcnt lgkmcnt(0)
	s_barrier
	ds_read2_b32 v[8:9], v6 offset1:65
	ds_read2_b32 v[10:11], v6 offset0:130 offset1:195
	ds_read2_b32 v[12:13], v17 offset0:4 offset1:69
	ds_read2_b32 v[14:15], v17 offset0:134 offset1:199
	s_waitcnt lgkmcnt(3)
	v_cvt_pk_bf16_f32 v8, v8, v9
	s_waitcnt lgkmcnt(2)
	v_cvt_pk_bf16_f32 v9, v10, v11
	s_waitcnt lgkmcnt(1)
	v_cvt_pk_bf16_f32 v10, v12, v13
	s_waitcnt lgkmcnt(0)
	v_cvt_pk_bf16_f32 v11, v14, v15
	global_store_dwordx4 v[0:1], v[8:11], off
	s_barrier
	s_cbranch_scc0 .LBB0_263

; DEV void cvt_job(const float* __restrict__ src, int K, int N, int ldsrc, bf16_t* __restrict__ dst, int nperm, int& tbase, char* smem) {
;     ...
;   for (int t = first; t < cnt; t += G) {
;     const int kt = t % nkt, nt = t / nkt;
;     const int ty = tid >> 4, tx = tid & 15;
;     const int n = nt * 64 + tx * 4;
;     const int sc = (n < nperm) ? conv_srccol(n) : n;
; #pragma unroll
;     for (int i = 0; i < 2; ++i) {
;       const int k = ty + 32 * i;
;       const float4 v = *(const float4*)(src + (size_t)(kt * 64 + k) * ldsrc + sc);
;       float* d = lds + k * 65 + tx * 4;
;       d[0] = v.x; d[1] = v.y; d[2] = v.z; d[3] = v.w;
;     }
;     __syncthreads();
;     {
;       const int nn = tid >> 3, kc = tid & 7;
;       float v[8];
; #pragma unroll
;       for (int j = 0; j < 8; ++j) v[j] = lds[(kc * 8 + j) * 65 + nn];
;       uint4 o;
;       o.x = pk2(v[0], v[1]); o.y = pk2(v[2], v[3]); o.z = pk2(v[4], v[5]); o.w = pk2(v[6], v[7]);
;       *(uint4*)(dst + (size_t)(nt * 64 + nn) * K + kt * 64 + kc * 8) = o;
;     }
;     __syncthreads();
.LBB0_265:
	s_mul_i32 s100, s92, 3
	s_add_i32 s100, s100, s1
	s_cmpk_lt_i32 s100, 0x80
	s_cselect_b32 s100, 0x6000, 0
	s_mov_b32 s101, 0
	s_lshl_b32 s31, s31, 9
	s_sub_i32 s36, s0, s31
	v_add_u32_e32 v12, s36, v2
	v_ashrrev_i32_e32 v1, 31, v0
	v_ashrrev_i32_e32 v13, 31, v12
	v_lshl_add_u64 v[0:1], v[0:1], 2, s[18:19]
	v_lshlrev_b64 v[8:9], 12, v[12:13]
	v_add_u32_e32 v12, 32, v12
	v_lshl_add_u64 v[8:9], v[0:1], 0, v[8:9]
	v_ashrrev_i32_e32 v13, 31, v12
	v_lshl_add_u64 v[242:243], v[8:9], 0, s[100:101]
	global_load_dwordx4 v[8:11], v[8:9], off
	v_lshlrev_b64 v[12:13], 12, v[12:13]
	v_lshl_add_u64 v[0:1], v[0:1], 0, v[12:13]
	v_lshl_add_u64 v[244:245], v[0:1], 0, s[100:101]
	global_load_dwordx4 v[12:15], v[0:1], off
	global_load_dword v238, v[242:243], off
	global_load_dword v239, v[244:245], off
	v_add_u32_e32 v7, 0x2080, v5
	v_add_u32_e32 v16, 0x2088, v5
	v_add_u32_e32 v17, 0x400, v6
	v_add_u32_e32 v0, s30, v4
	v_ashrrev_i32_e32 v1, 31, v0
	v_readlane_b32 s30, v251, 15
	v_lshlrev_b64 v[0:1], 10, v[0:1]
	v_readlane_b32 s31, v251, 16
	s_ashr_i32 s37, s36, 31
	s_add_i32 s1, s1, s92
	v_lshl_add_u64 v[0:1], s[30:31], 0, v[0:1]
	s_add_i32 s0, s0, s33
	v_lshl_add_u64 v[0:1], s[36:37], 1, v[0:1]
	s_cmpk_lt_i32 s1, 0x80
	v_lshl_add_u64 v[0:1], v[0:1], 0, v[96:97]
	s_waitcnt vmcnt(3)
	ds_write2_b32 v5, v8, v9 offset1:1
	ds_write2_b32 v5, v10, v11 offset0:2 offset1:3
	s_waitcnt vmcnt(2)
	ds_write2_b32 v7, v12, v13 offset1:1
	ds_write2_b32 v16, v14, v15 offset1:1
	s_waitcnt lgkmcnt(0)
	s_barrier
	ds_read2_b32 v[8:9], v6 offset1:65
	ds_read2_b32 v[10:11], v6 offset0:130 offset1:195
	ds_read2_b32 v[12:13], v17 offset0:4 offset1:69
	ds_read2_b32 v[14:15], v17 offset0:134 offset1:199
	s_waitcnt lgkmcnt(3)
	v_cvt_pk_bf16_f32 v8, v8, v9
	s_waitcnt lgkmcnt(2)
	v_cvt_pk_bf16_f32 v9, v10, v11
	s_waitcnt lgkmcnt(1)
	v_cvt_pk_bf16_f32 v10, v12, v13
	s_waitcnt lgkmcnt(0)
	v_cvt_pk_bf16_f32 v11, v14, v15
	global_store_dwordx4 v[0:1], v[8:11], off
	s_barrier
	s_cbranch_scc0 .LBB0_268

; DEV void cvt_job(const float* __restrict__ src, int K, int N, int ldsrc, bf16_t* __restrict__ dst, int nperm, int& tbase, char* smem) {
;     ...
;   for (int t = first; t < cnt; t += G) {
;     const int kt = t % nkt, nt = t / nkt;
;     const int ty = tid >> 4, tx = tid & 15;
;     const int n = nt * 64 + tx * 4;
;     const int sc = (n < nperm) ? conv_srccol(n) : n;
; #pragma unroll
;     for (int i = 0; i < 2; ++i) {
;       const int k = ty + 32 * i;
;       const float4 v = *(const float4*)(src + (size_t)(kt * 64 + k) * ldsrc + sc);
;       float* d = lds + k * 65 + tx * 4;
;       d[0] = v.x; d[1] = v.y; d[2] = v.z; d[3] = v.w;
;     }
;     __syncthreads();
;     {
;       const int nn = tid >> 3, kc = tid & 7;
;       float v[8];
; #pragma unroll
;       for (int j = 0; j < 8; ++j) v[j] = lds[(kc * 8 + j) * 65 + nn];
;       uint4 o;
;       o.x = pk2(v[0], v[1]); o.y = pk2(v[2], v[3]); o.z = pk2(v[4], v[5]); o.w = pk2(v[6], v[7]);
;       *(uint4*)(dst + (size_t)(nt * 64 + nn) * K + kt * 64 + kc * 8) = o;
;     }
;     __syncthreads();
.LBB0_615:
	s_or_b64 exec, exec, s[30:31]
	s_mul_i32 s100, s92, 3
	s_add_i32 s100, s100, s37
	s_cmpk_lt_i32 s100, 0x460
	s_cselect_b32 s100, 0x3000, 0
	s_mov_b32 s101, 0
	s_lshl_b32 s30, s39, 10
	s_sub_i32 s30, s36, s30
	v_ashrrev_i32_e32 v1, 31, v0
	v_lshl_add_u64 v[0:1], v[0:1], 2, s[0:1]
	v_add_u32_e32 v7, s30, v2
	v_mad_i64_i32 v[8:9], s[40:41], v7, s29, v[0:1]
	v_lshl_add_u64 v[242:243], v[8:9], 0, s[100:101]
	global_load_dwordx4 v[8:11], v[8:9], off
	v_add_u32_e32 v7, 32, v7
	v_mad_i64_i32 v[0:1], s[40:41], v7, s29, v[0:1]
	v_lshl_add_u64 v[244:245], v[0:1], 0, s[100:101]
	global_load_dwordx4 v[12:15], v[0:1], off
	global_load_dword v238, v[242:243], off
	global_load_dword v239, v[244:245], off
	v_add_u32_e32 v7, 0x2080, v5
	v_add_u32_e32 v16, 0x2088, v5
	v_add_u32_e32 v17, 0x400, v6
	v_add_u32_e32 v0, s38, v4
	v_ashrrev_i32_e32 v1, 31, v0
	v_lshlrev_b64 v[0:1], 11, v[0:1]
	s_ashr_i32 s31, s30, 31
	v_lshl_add_u64 v[0:1], s[62:63], 0, v[0:1]
	s_add_i32 s37, s37, s92
	s_add_i32 s36, s36, s33
	v_lshl_add_u64 v[0:1], s[30:31], 1, v[0:1]
	s_cmpk_lt_i32 s37, 0x460
	v_lshl_add_u64 v[0:1], v[0:1], 0, v[96:97]
	s_waitcnt vmcnt(3)
	ds_write2_b32 v5, v8, v9 offset1:1
	ds_write2_b32 v5, v10, v11 offset0:2 offset1:3
	s_waitcnt vmcnt(2)
	ds_write2_b32 v7, v12, v13 offset1:1
	ds_write2_b32 v16, v14, v15 offset1:1
	s_waitcnt lgkmcnt(0)
	s_barrier
	ds_read2_b32 v[8:9], v6 offset1:65
	ds_read2_b32 v[10:11], v6 offset0:130 offset1:195
	ds_read2_b32 v[12:13], v17 offset0:4 offset1:69
	ds_read2_b32 v[14:15], v17 offset0:134 offset1:199
	s_waitcnt lgkmcnt(3)
	v_cvt_pk_bf16_f32 v8, v8, v9
	s_waitcnt lgkmcnt(2)
	v_cvt_pk_bf16_f32 v9, v10, v11
	s_waitcnt lgkmcnt(1)
	v_cvt_pk_bf16_f32 v10, v12, v13
	s_waitcnt lgkmcnt(0)
	v_cvt_pk_bf16_f32 v11, v14, v15
	global_store_dwordx4 v[0:1], v[8:11], off
	s_barrier
	s_cbranch_scc0 .LBB0_619

; DEV void cvt_job(const float* __restrict__ src, int K, int N, int ldsrc, bf16_t* __restrict__ dst, int nperm, int& tbase, char* smem) {
;     ...
;   for (int t = first; t < cnt; t += G) {
;     const int kt = t % nkt, nt = t / nkt;
;     const int ty = tid >> 4, tx = tid & 15;
;     const int n = nt * 64 + tx * 4;
;     const int sc = (n < nperm) ? conv_srccol(n) : n;
; #pragma unroll
;     for (int i = 0; i < 2; ++i) {
;       const int k = ty + 32 * i;
;       const float4 v = *(const float4*)(src + (size_t)(kt * 64 + k) * ldsrc + sc);
;       float* d = lds + k * 65 + tx * 4;
;       d[0] = v.x; d[1] = v.y; d[2] = v.z; d[3] = v.w;
;     }
;     __syncthreads();
;     {
;       const int nn = tid >> 3, kc = tid & 7;
;       float v[8];
; #pragma unroll
;       for (int j = 0; j < 8; ++j) v[j] = lds[(kc * 8 + j) * 65 + nn];
;       uint4 o;
;       o.x = pk2(v[0], v[1]); o.y = pk2(v[2], v[3]); o.z = pk2(v[4], v[5]); o.w = pk2(v[6], v[7]);
;       *(uint4*)(dst + (size_t)(nt * 64 + nn) * K + kt * 64 + kc * 8) = o;
;     }
;     __syncthreads();
.LBB0_621:
	s_mul_i32 s100, s92, 3
	s_add_i32 s100, s100, s31
	s_cmpk_lt_i32 s100, 0x300
	s_cselect_b32 s100, 0x3000, 0
	s_mov_b32 s101, 0
	s_lshl_b32 s37, s37, 10
	s_sub_i32 s38, s30, s37
	v_ashrrev_i32_e32 v1, 31, v0
	v_lshl_add_u64 v[0:1], v[0:1], 2, s[0:1]
	v_add_u32_e32 v7, s38, v2
	v_mad_i64_i32 v[8:9], s[40:41], v7, s29, v[0:1]
	v_lshl_add_u64 v[242:243], v[8:9], 0, s[100:101]
	global_load_dwordx4 v[8:11], v[8:9], off
	v_add_u32_e32 v7, 32, v7
	v_mad_i64_i32 v[0:1], s[40:41], v7, s29, v[0:1]
	v_lshl_add_u64 v[244:245], v[0:1], 0, s[100:101]
	global_load_dwordx4 v[12:15], v[0:1], off
	global_load_dword v238, v[242:243], off
	global_load_dword v239, v[244:245], off
	v_add_u32_e32 v7, 0x2080, v5
	v_add_u32_e32 v16, 0x2088, v5
	v_add_u32_e32 v17, 0x400, v6
	v_add_u32_e32 v0, s36, v4
	v_ashrrev_i32_e32 v1, 31, v0
	v_readlane_b32 s36, v251, 5
	v_lshlrev_b64 v[0:1], 11, v[0:1]
	v_readlane_b32 s37, v251, 6
	s_ashr_i32 s39, s38, 31
	s_add_i32 s31, s31, s92
	v_lshl_add_u64 v[0:1], s[36:37], 0, v[0:1]
	s_add_i32 s30, s30, s33
	v_lshl_add_u64 v[0:1], s[38:39], 1, v[0:1]
	s_cmpk_lt_i32 s31, 0x300
	v_lshl_add_u64 v[0:1], v[0:1], 0, v[96:97]
	s_waitcnt vmcnt(3)
	ds_write2_b32 v5, v8, v9 offset1:1
	ds_write2_b32 v5, v10, v11 offset0:2 offset1:3
	s_waitcnt vmcnt(2)
	ds_write2_b32 v7, v12, v13 offset1:1
	ds_write2_b32 v16, v14, v15 offset1:1
	s_waitcnt lgkmcnt(0)
	s_barrier
	ds_read2_b32 v[8:9], v6 offset1:65
	ds_read2_b32 v[10:11], v6 offset0:130 offset1:195
	ds_read2_b32 v[12:13], v17 offset0:4 offset1:69
	ds_read2_b32 v[14:15], v17 offset0:134 offset1:199
	s_waitcnt lgkmcnt(3)
	v_cvt_pk_bf16_f32 v8, v8, v9
	s_waitcnt lgkmcnt(2)
	v_cvt_pk_bf16_f32 v9, v10, v11
	s_waitcnt lgkmcnt(1)
	v_cvt_pk_bf16_f32 v10, v12, v13
	s_waitcnt lgkmcnt(0)
	v_cvt_pk_bf16_f32 v11, v14, v15
	global_store_dwordx4 v[0:1], v[8:11], off
	s_barrier
	s_cbranch_scc0 .LBB0_624

; DEV void cvt_job(const float* __restrict__ src, int K, int N, int ldsrc, bf16_t* __restrict__ dst, int nperm, int& tbase, char* smem) {
;     ...
;   for (int t = first; t < cnt; t += G) {
;     const int kt = t % nkt, nt = t / nkt;
;     const int ty = tid >> 4, tx = tid & 15;
;     const int n = nt * 64 + tx * 4;
;     const int sc = (n < nperm) ? conv_srccol(n) : n;
; #pragma unroll
;     for (int i = 0; i < 2; ++i) {
;       const int k = ty + 32 * i;
;       const float4 v = *(const float4*)(src + (size_t)(kt * 64 + k) * ldsrc + sc);
;       float* d = lds + k * 65 + tx * 4;
;       d[0] = v.x; d[1] = v.y; d[2] = v.z; d[3] = v.w;
;     }
;     __syncthreads();
;     {
;       const int nn = tid >> 3, kc = tid & 7;
;       float v[8];
; #pragma unroll
;       for (int j = 0; j < 8; ++j) v[j] = lds[(kc * 8 + j) * 65 + nn];
;       uint4 o;
;       o.x = pk2(v[0], v[1]); o.y = pk2(v[2], v[3]); o.z = pk2(v[4], v[5]); o.w = pk2(v[6], v[7]);
;       *(uint4*)(dst + (size_t)(nt * 64 + nn) * K + kt * 64 + kc * 8) = o;
;     }
;     __syncthreads();
.LBB0_626:
	s_mul_i32 s100, s92, 3
	s_add_i32 s100, s100, s37
	s_cmpk_lt_i32 s100, 0x400
	s_cselect_b32 s100, 0x3000, 0
	s_mov_b32 s101, 0
	s_lshl_b32 s39, s39, 10
	s_sub_i32 s40, s36, s39
	v_add_u32_e32 v12, s40, v2
	v_ashrrev_i32_e32 v1, 31, v0
	v_ashrrev_i32_e32 v13, 31, v12
	v_lshl_add_u64 v[0:1], v[0:1], 2, s[30:31]
	v_lshlrev_b64 v[8:9], 14, v[12:13]
	v_add_u32_e32 v12, 32, v12
	v_lshl_add_u64 v[8:9], v[0:1], 0, v[8:9]
	v_ashrrev_i32_e32 v13, 31, v12
	v_lshl_add_u64 v[242:243], v[8:9], 0, s[100:101]
	global_load_dwordx4 v[8:11], v[8:9], off
	v_lshlrev_b64 v[12:13], 14, v[12:13]
	v_lshl_add_u64 v[0:1], v[0:1], 0, v[12:13]
	v_lshl_add_u64 v[244:245], v[0:1], 0, s[100:101]
	global_load_dwordx4 v[12:15], v[0:1], off
	global_load_dword v238, v[242:243], off
	global_load_dword v239, v[244:245], off
	v_add_u32_e32 v7, 0x2080, v5
	v_add_u32_e32 v16, 0x2088, v5
	v_add_u32_e32 v17, 0x400, v6
	v_add_u32_e32 v0, s38, v4
	v_ashrrev_i32_e32 v1, 31, v0
	v_readlane_b32 s38, v251, 7
	v_lshlrev_b64 v[0:1], 11, v[0:1]
	v_readlane_b32 s39, v251, 8
	s_ashr_i32 s41, s40, 31
	s_add_i32 s37, s37, s92
	v_lshl_add_u64 v[0:1], s[38:39], 0, v[0:1]
	s_add_i32 s36, s36, s33
	v_lshl_add_u64 v[0:1], s[40:41], 1, v[0:1]
	s_cmpk_lt_i32 s37, 0x400
	v_lshl_add_u64 v[0:1], v[0:1], 0, v[96:97]
	s_waitcnt vmcnt(3)
	ds_write2_b32 v5, v8, v9 offset1:1
	ds_write2_b32 v5, v10, v11 offset0:2 offset1:3
	s_waitcnt vmcnt(2)
	ds_write2_b32 v7, v12, v13 offset1:1
	ds_write2_b32 v16, v14, v15 offset1:1
	s_waitcnt lgkmcnt(0)
	s_barrier
	ds_read2_b32 v[8:9], v6 offset1:65
	ds_read2_b32 v[10:11], v6 offset0:130 offset1:195
	ds_read2_b32 v[12:13], v17 offset0:4 offset1:69
	ds_read2_b32 v[14:15], v17 offset0:134 offset1:199
	s_waitcnt lgkmcnt(3)
	v_cvt_pk_bf16_f32 v8, v8, v9
	s_waitcnt lgkmcnt(2)
	v_cvt_pk_bf16_f32 v9, v10, v11
	s_waitcnt lgkmcnt(1)
	v_cvt_pk_bf16_f32 v10, v12, v13
	s_waitcnt lgkmcnt(0)
	v_cvt_pk_bf16_f32 v11, v14, v15
	global_store_dwordx4 v[0:1], v[8:11], off
	s_barrier
	s_cbranch_scc0 .LBB0_629

; DEV void cvt_job(const float* __restrict__ src, int K, int N, int ldsrc, bf16_t* __restrict__ dst, int nperm, int& tbase, char* smem) {
;     ...
;   for (int t = first; t < cnt; t += G) {
;     const int kt = t % nkt, nt = t / nkt;
;     const int ty = tid >> 4, tx = tid & 15;
;     const int n = nt * 64 + tx * 4;
;     const int sc = (n < nperm) ? conv_srccol(n) : n;
; #pragma unroll
;     for (int i = 0; i < 2; ++i) {
;       const int k = ty + 32 * i;
;       const float4 v = *(const float4*)(src + (size_t)(kt * 64 + k) * ldsrc + sc);
;       float* d = lds + k * 65 + tx * 4;
;       d[0] = v.x; d[1] = v.y; d[2] = v.z; d[3] = v.w;
;     }
;     __syncthreads();
;     {
;       const int nn = tid >> 3, kc = tid & 7;
;       float v[8];
; #pragma unroll
;       for (int j = 0; j < 8; ++j) v[j] = lds[(kc * 8 + j) * 65 + nn];
;       uint4 o;
;       o.x = pk2(v[0], v[1]); o.y = pk2(v[2], v[3]); o.z = pk2(v[4], v[5]); o.w = pk2(v[6], v[7]);
;       *(uint4*)(dst + (size_t)(nt * 64 + nn) * K + kt * 64 + kc * 8) = o;
;     }
;     __syncthreads();
.LBB0_631:
	s_mul_i32 s100, s92, 3
	s_add_i32 s100, s100, s31
	s_cmpk_lt_i32 s100, 0x400
	s_cselect_b32 s100, 0xc00, 0
	s_mov_b32 s101, 0
	s_lshl_b32 s37, s37, 12
	s_sub_i32 s38, s30, s37
	v_add_u32_e32 v12, s38, v2
	v_ashrrev_i32_e32 v1, 31, v0
	v_ashrrev_i32_e32 v13, 31, v12
	v_lshl_add_u64 v[0:1], v[0:1], 2, s[0:1]
	v_lshlrev_b64 v[8:9], 12, v[12:13]
	v_add_u32_e32 v12, 32, v12
	v_lshl_add_u64 v[8:9], v[0:1], 0, v[8:9]
	v_ashrrev_i32_e32 v13, 31, v12
	v_lshl_add_u64 v[242:243], v[8:9], 0, s[100:101]
	global_load_dwordx4 v[8:11], v[8:9], off
	v_lshlrev_b64 v[12:13], 12, v[12:13]
	v_lshl_add_u64 v[0:1], v[0:1], 0, v[12:13]
	v_lshl_add_u64 v[244:245], v[0:1], 0, s[100:101]
	global_load_dwordx4 v[12:15], v[0:1], off
	global_load_dword v238, v[242:243], off
	global_load_dword v239, v[244:245], off
	v_add_u32_e32 v7, 0x2080, v5
	v_add_u32_e32 v16, 0x2088, v5
	v_add_u32_e32 v17, 0x400, v6
	v_add_u32_e32 v0, s36, v4
	v_ashrrev_i32_e32 v1, 31, v0
	v_readlane_b32 s36, v251, 9
	v_lshlrev_b64 v[0:1], 13, v[0:1]
	v_readlane_b32 s37, v251, 10
	s_ashr_i32 s39, s38, 31
	s_add_i32 s31, s31, s92
	v_lshl_add_u64 v[0:1], s[36:37], 0, v[0:1]
	s_add_i32 s30, s30, s33
	v_lshl_add_u64 v[0:1], s[38:39], 1, v[0:1]
	s_cmpk_lt_i32 s31, 0x400
	v_lshl_add_u64 v[0:1], v[0:1], 0, v[96:97]
	s_waitcnt vmcnt(3)
	ds_write2_b32 v5, v8, v9 offset1:1
	ds_write2_b32 v5, v10, v11 offset0:2 offset1:3
	s_waitcnt vmcnt(2)
	ds_write2_b32 v7, v12, v13 offset1:1
	ds_write2_b32 v16, v14, v15 offset1:1
	s_waitcnt lgkmcnt(0)
	s_barrier
	ds_read2_b32 v[8:9], v6 offset1:65
	ds_read2_b32 v[10:11], v6 offset0:130 offset1:195
	ds_read2_b32 v[12:13], v17 offset0:4 offset1:69
	ds_read2_b32 v[14:15], v17 offset0:134 offset1:199
	s_waitcnt lgkmcnt(3)
	v_cvt_pk_bf16_f32 v8, v8, v9
	s_waitcnt lgkmcnt(2)
	v_cvt_pk_bf16_f32 v9, v10, v11
	s_waitcnt lgkmcnt(1)
	v_cvt_pk_bf16_f32 v10, v12, v13
	s_waitcnt lgkmcnt(0)
	v_cvt_pk_bf16_f32 v11, v14, v15
	global_store_dwordx4 v[0:1], v[8:11], off
	s_barrier
	s_cbranch_scc0 .LBB0_634

; DEV void cvt_job(const float* __restrict__ src, int K, int N, int ldsrc, bf16_t* __restrict__ dst, int nperm, int& tbase, char* smem) {
;     ...
;   for (int t = first; t < cnt; t += G) {
;     const int kt = t % nkt, nt = t / nkt;
;     const int ty = tid >> 4, tx = tid & 15;
;     const int n = nt * 64 + tx * 4;
;     const int sc = (n < nperm) ? conv_srccol(n) : n;
; #pragma unroll
;     for (int i = 0; i < 2; ++i) {
;       const int k = ty + 32 * i;
;       const float4 v = *(const float4*)(src + (size_t)(kt * 64 + k) * ldsrc + sc);
;       float* d = lds + k * 65 + tx * 4;
;       d[0] = v.x; d[1] = v.y; d[2] = v.z; d[3] = v.w;
;     }
;     __syncthreads();
;     {
;       const int nn = tid >> 3, kc = tid & 7;
;       float v[8];
; #pragma unroll
;       for (int j = 0; j < 8; ++j) v[j] = lds[(kc * 8 + j) * 65 + nn];
;       uint4 o;
;       o.x = pk2(v[0], v[1]); o.y = pk2(v[2], v[3]); o.z = pk2(v[4], v[5]); o.w = pk2(v[6], v[7]);
;       *(uint4*)(dst + (size_t)(nt * 64 + nn) * K + kt * 64 + kc * 8) = o;
;     }
;     __syncthreads();
.LBB0_636:
	s_mul_i32 s100, s92, 3
	s_add_i32 s100, s100, s31
	s_cmpk_lt_i32 s100, 0x100
	s_cselect_b32 s100, 0x3000, 0
	s_mov_b32 s101, 0
	s_lshl_b32 s37, s37, 10
	s_sub_i32 s38, s30, s37
	v_add_u32_e32 v12, s38, v2
	v_ashrrev_i32_e32 v1, 31, v0
	v_ashrrev_i32_e32 v13, 31, v12
	v_lshl_add_u64 v[0:1], v[0:1], 2, s[0:1]
	v_lshlrev_b64 v[8:9], 12, v[12:13]
	v_add_u32_e32 v12, 32, v12
	v_lshl_add_u64 v[8:9], v[0:1], 0, v[8:9]
	v_ashrrev_i32_e32 v13, 31, v12
	v_lshl_add_u64 v[242:243], v[8:9], 0, s[100:101]
	global_load_dwordx4 v[8:11], v[8:9], off
	v_lshlrev_b64 v[12:13], 12, v[12:13]
	v_lshl_add_u64 v[0:1], v[0:1], 0, v[12:13]
	v_lshl_add_u64 v[244:245], v[0:1], 0, s[100:101]
	global_load_dwordx4 v[12:15], v[0:1], off
	global_load_dword v238, v[242:243], off
	global_load_dword v239, v[244:245], off
	v_add_u32_e32 v7, 0x2080, v5
	v_add_u32_e32 v16, 0x2088, v5
	v_add_u32_e32 v17, 0x400, v6
	v_add_u32_e32 v0, s36, v4
	v_ashrrev_i32_e32 v1, 31, v0
	v_readlane_b32 s36, v251, 11
	v_lshlrev_b64 v[0:1], 11, v[0:1]
	v_readlane_b32 s37, v251, 12
	s_ashr_i32 s39, s38, 31
	s_add_i32 s31, s31, s92
	v_lshl_add_u64 v[0:1], s[36:37], 0, v[0:1]
	s_add_i32 s30, s30, s33
	v_lshl_add_u64 v[0:1], s[38:39], 1, v[0:1]
	s_cmpk_lt_i32 s31, 0x100
	v_lshl_add_u64 v[0:1], v[0:1], 0, v[96:97]
	s_waitcnt vmcnt(3)
	ds_write2_b32 v5, v8, v9 offset1:1
	ds_write2_b32 v5, v10, v11 offset0:2 offset1:3
	s_waitcnt vmcnt(2)
	ds_write2_b32 v7, v12, v13 offset1:1
	ds_write2_b32 v16, v14, v15 offset1:1
	s_waitcnt lgkmcnt(0)
	s_barrier
	ds_read2_b32 v[8:9], v6 offset1:65
	ds_read2_b32 v[10:11], v6 offset0:130 offset1:195
	ds_read2_b32 v[12:13], v17 offset0:4 offset1:69
	ds_read2_b32 v[14:15], v17 offset0:134 offset1:199
	s_waitcnt lgkmcnt(3)
	v_cvt_pk_bf16_f32 v8, v8, v9
	s_waitcnt lgkmcnt(2)
	v_cvt_pk_bf16_f32 v9, v10, v11
	s_waitcnt lgkmcnt(1)
	v_cvt_pk_bf16_f32 v10, v12, v13
	s_waitcnt lgkmcnt(0)
	v_cvt_pk_bf16_f32 v11, v14, v15
	global_store_dwordx4 v[0:1], v[8:11], off
	s_barrier
	s_cbranch_scc0 .LBB0_639

; DEV void cvt_job(const float* __restrict__ src, int K, int N, int ldsrc, bf16_t* __restrict__ dst, int nperm, int& tbase, char* smem) {
;     ...
;   for (int t = first; t < cnt; t += G) {
;     const int kt = t % nkt, nt = t / nkt;
;     const int ty = tid >> 4, tx = tid & 15;
;     const int n = nt * 64 + tx * 4;
;     const int sc = (n < nperm) ? conv_srccol(n) : n;
; #pragma unroll
;     for (int i = 0; i < 2; ++i) {
;       const int k = ty + 32 * i;
;       const float4 v = *(const float4*)(src + (size_t)(kt * 64 + k) * ldsrc + sc);
;       float* d = lds + k * 65 + tx * 4;
;       d[0] = v.x; d[1] = v.y; d[2] = v.z; d[3] = v.w;
;     }
;     __syncthreads();
;     {
;       const int nn = tid >> 3, kc = tid & 7;
;       float v[8];
; #pragma unroll
;       for (int j = 0; j < 8; ++j) v[j] = lds[(kc * 8 + j) * 65 + nn];
;       uint4 o;
;       o.x = pk2(v[0], v[1]); o.y = pk2(v[2], v[3]); o.z = pk2(v[4], v[5]); o.w = pk2(v[6], v[7]);
;       *(uint4*)(dst + (size_t)(nt * 64 + nn) * K + kt * 64 + kc * 8) = o;
;     }
;     __syncthreads();
.LBB0_641:
	s_mul_i32 s100, s92, 3
	s_add_i32 s100, s100, s37
	s_cmpk_lt_i32 s100, 0x80
	s_cselect_b32 s100, 0x6000, 0
	s_mov_b32 s101, 0
	s_lshl_b32 s39, s39, 9
	s_sub_i32 s40, s36, s39
	v_add_u32_e32 v12, s40, v2
	v_ashrrev_i32_e32 v1, 31, v0
	v_ashrrev_i32_e32 v13, 31, v12
	v_lshl_add_u64 v[0:1], v[0:1], 2, s[30:31]
	v_lshlrev_b64 v[8:9], 12, v[12:13]
	v_add_u32_e32 v12, 32, v12
	v_lshl_add_u64 v[8:9], v[0:1], 0, v[8:9]
	v_ashrrev_i32_e32 v13, 31, v12
	v_lshl_add_u64 v[242:243], v[8:9], 0, s[100:101]
	global_load_dwordx4 v[8:11], v[8:9], off
	v_lshlrev_b64 v[12:13], 12, v[12:13]
	v_lshl_add_u64 v[0:1], v[0:1], 0, v[12:13]
	v_lshl_add_u64 v[244:245], v[0:1], 0, s[100:101]
	global_load_dwordx4 v[12:15], v[0:1], off
	global_load_dword v238, v[242:243], off
	global_load_dword v239, v[244:245], off
	v_add_u32_e32 v7, 0x2080, v5
	v_add_u32_e32 v16, 0x2088, v5
	v_add_u32_e32 v17, 0x400, v6
	v_add_u32_e32 v0, s38, v4
	v_ashrrev_i32_e32 v1, 31, v0
	v_readlane_b32 s38, v251, 13
	v_lshlrev_b64 v[0:1], 10, v[0:1]
	v_readlane_b32 s39, v251, 14
	s_ashr_i32 s41, s40, 31
	s_add_i32 s37, s37, s92
	v_lshl_add_u64 v[0:1], s[38:39], 0, v[0:1]
	s_add_i32 s36, s36, s33
	v_lshl_add_u64 v[0:1], s[40:41], 1, v[0:1]
	s_cmpk_lt_i32 s37, 0x80
	v_lshl_add_u64 v[0:1], v[0:1], 0, v[96:97]
	s_waitcnt vmcnt(3)
	ds_write2_b32 v5, v8, v9 offset1:1
	ds_write2_b32 v5, v10, v11 offset0:2 offset1:3
	s_waitcnt vmcnt(2)
	ds_write2_b32 v7, v12, v13 offset1:1
	ds_write2_b32 v16, v14, v15 offset1:1
	s_waitcnt lgkmcnt(0)
	s_barrier
	ds_read2_b32 v[8:9], v6 offset1:65
	ds_read2_b32 v[10:11], v6 offset0:130 offset1:195
	ds_read2_b32 v[12:13], v17 offset0:4 offset1:69
	ds_read2_b32 v[14:15], v17 offset0:134 offset1:199
	s_waitcnt lgkmcnt(3)
	v_cvt_pk_bf16_f32 v8, v8, v9
	s_waitcnt lgkmcnt(2)
	v_cvt_pk_bf16_f32 v9, v10, v11
	s_waitcnt lgkmcnt(1)
	v_cvt_pk_bf16_f32 v10, v12, v13
	s_waitcnt lgkmcnt(0)
	v_cvt_pk_bf16_f32 v11, v14, v15
	global_store_dwordx4 v[0:1], v[8:11], off
	s_barrier
	s_cbranch_scc0 .LBB0_731

; DEV void cvt_job(const float* __restrict__ src, int K, int N, int ldsrc, bf16_t* __restrict__ dst, int nperm, int& tbase, char* smem) {
;     ...
;   for (int t = first; t < cnt; t += G) {
;     const int kt = t % nkt, nt = t / nkt;
;     const int ty = tid >> 4, tx = tid & 15;
;     const int n = nt * 64 + tx * 4;
;     const int sc = (n < nperm) ? conv_srccol(n) : n;
; #pragma unroll
;     for (int i = 0; i < 2; ++i) {
;       const int k = ty + 32 * i;
;       const float4 v = *(const float4*)(src + (size_t)(kt * 64 + k) * ldsrc + sc);
;       float* d = lds + k * 65 + tx * 4;
;       d[0] = v.x; d[1] = v.y; d[2] = v.z; d[3] = v.w;
;     }
;     __syncthreads();
;     {
;       const int nn = tid >> 3, kc = tid & 7;
;       float v[8];
; #pragma unroll
;       for (int j = 0; j < 8; ++j) v[j] = lds[(kc * 8 + j) * 65 + nn];
;       uint4 o;
;       o.x = pk2(v[0], v[1]); o.y = pk2(v[2], v[3]); o.z = pk2(v[4], v[5]); o.w = pk2(v[6], v[7]);
;       *(uint4*)(dst + (size_t)(nt * 64 + nn) * K + kt * 64 + kc * 8) = o;
;     }
;     __syncthreads();
.LBB0_734:
	s_mul_i32 s100, s92, 3
	s_add_i32 s100, s100, s37
	s_cmpk_lt_i32 s100, 0x80
	s_cselect_b32 s100, 0x6000, 0
	s_mov_b32 s101, 0
	s_lshl_b32 s39, s39, 9
	s_sub_i32 s40, s36, s39
	v_add_u32_e32 v12, s40, v2
	v_ashrrev_i32_e32 v1, 31, v0
	v_ashrrev_i32_e32 v13, 31, v12
	v_lshl_add_u64 v[0:1], v[0:1], 2, s[30:31]
	v_lshlrev_b64 v[8:9], 12, v[12:13]
	v_add_u32_e32 v12, 32, v12
	v_lshl_add_u64 v[8:9], v[0:1], 0, v[8:9]
	v_ashrrev_i32_e32 v13, 31, v12
	v_lshl_add_u64 v[242:243], v[8:9], 0, s[100:101]
	global_load_dwordx4 v[8:11], v[8:9], off
	v_lshlrev_b64 v[12:13], 12, v[12:13]
	v_lshl_add_u64 v[0:1], v[0:1], 0, v[12:13]
	v_lshl_add_u64 v[244:245], v[0:1], 0, s[100:101]
	global_load_dwordx4 v[12:15], v[0:1], off
	global_load_dword v238, v[242:243], off
	global_load_dword v239, v[244:245], off
	v_add_u32_e32 v7, 0x2080, v5
	v_add_u32_e32 v16, 0x2088, v5
	v_add_u32_e32 v17, 0x400, v6
	v_add_u32_e32 v0, s38, v4
	v_ashrrev_i32_e32 v1, 31, v0
	v_lshlrev_b64 v[0:1], 10, v[0:1]
	s_ashr_i32 s41, s40, 31
	v_lshl_add_u64 v[0:1], s[66:67], 0, v[0:1]
	s_add_i32 s37, s37, s92
	s_add_i32 s36, s36, s33
	v_lshl_add_u64 v[0:1], s[40:41], 1, v[0:1]
	s_cmpk_lt_i32 s37, 0x80
	v_lshl_add_u64 v[0:1], v[0:1], 0, v[96:97]
	s_waitcnt vmcnt(3)
	ds_write2_b32 v5, v8, v9 offset1:1
	ds_write2_b32 v5, v10, v11 offset0:2 offset1:3
	s_waitcnt vmcnt(2)
	ds_write2_b32 v7, v12, v13 offset1:1
	ds_write2_b32 v16, v14, v15 offset1:1
	s_waitcnt lgkmcnt(0)
	s_barrier
	ds_read2_b32 v[8:9], v6 offset1:65
	ds_read2_b32 v[10:11], v6 offset0:130 offset1:195
	ds_read2_b32 v[12:13], v17 offset0:4 offset1:69
	ds_read2_b32 v[14:15], v17 offset0:134 offset1:199
	s_waitcnt lgkmcnt(3)
	v_cvt_pk_bf16_f32 v8, v8, v9
	s_waitcnt lgkmcnt(2)
	v_cvt_pk_bf16_f32 v9, v10, v11
	s_waitcnt lgkmcnt(1)
	v_cvt_pk_bf16_f32 v10, v12, v13
	s_waitcnt lgkmcnt(0)
	v_cvt_pk_bf16_f32 v11, v14, v15
	global_store_dwordx4 v[0:1], v[8:11], off
	s_barrier
	s_cbranch_scc0 .LBB0_737

; DEV void cvt_job(const float* __restrict__ src, int K, int N, int ldsrc, bf16_t* __restrict__ dst, int nperm, int& tbase, char* smem) {
;     ...
;   for (int t = first; t < cnt; t += G) {
;     const int kt = t % nkt, nt = t / nkt;
;     const int ty = tid >> 4, tx = tid & 15;
;     const int n = nt * 64 + tx * 4;
;     const int sc = (n < nperm) ? conv_srccol(n) : n;
; #pragma unroll
;     for (int i = 0; i < 2; ++i) {
;       const int k = ty + 32 * i;
;       const float4 v = *(const float4*)(src + (size_t)(kt * 64 + k) * ldsrc + sc);
;       float* d = lds + k * 65 + tx * 4;
;       d[0] = v.x; d[1] = v.y; d[2] = v.z; d[3] = v.w;
;     }
;     __syncthreads();
;     {
;       const int nn = tid >> 3, kc = tid & 7;
;       float v[8];
; #pragma unroll
;       for (int j = 0; j < 8; ++j) v[j] = lds[(kc * 8 + j) * 65 + nn];
;       uint4 o;
;       o.x = pk2(v[0], v[1]); o.y = pk2(v[2], v[3]); o.z = pk2(v[4], v[5]); o.w = pk2(v[6], v[7]);
;       *(uint4*)(dst + (size_t)(nt * 64 + nn) * K + kt * 64 + kc * 8) = o;
;     }
;     __syncthreads();
.LBB0_740:
	s_mul_i32 s100, s92, 3
	s_add_i32 s100, s100, s31
	s_cmpk_lt_i32 s100, 0x80
	s_cselect_b32 s100, 0x6000, 0
	s_mov_b32 s101, 0
	s_lshl_b32 s37, s37, 9
	s_sub_i32 s38, s30, s37
	v_add_u32_e32 v12, s38, v2
	v_ashrrev_i32_e32 v1, 31, v0
	v_ashrrev_i32_e32 v13, 31, v12
	v_lshl_add_u64 v[0:1], v[0:1], 2, s[0:1]
	v_lshlrev_b64 v[8:9], 12, v[12:13]
	v_add_u32_e32 v12, 32, v12
	v_lshl_add_u64 v[8:9], v[0:1], 0, v[8:9]
	v_ashrrev_i32_e32 v13, 31, v12
	v_lshl_add_u64 v[242:243], v[8:9], 0, s[100:101]
	global_load_dwordx4 v[8:11], v[8:9], off
	v_lshlrev_b64 v[12:13], 12, v[12:13]
	v_lshl_add_u64 v[0:1], v[0:1], 0, v[12:13]
	v_lshl_add_u64 v[244:245], v[0:1], 0, s[100:101]
	global_load_dwordx4 v[12:15], v[0:1], off
	global_load_dword v238, v[242:243], off
	global_load_dword v239, v[244:245], off
	v_add_u32_e32 v7, 0x2080, v5
	v_add_u32_e32 v16, 0x2088, v5
	v_add_u32_e32 v17, 0x400, v6
	v_add_u32_e32 v0, s36, v4
	v_ashrrev_i32_e32 v1, 31, v0
	v_readlane_b32 s36, v251, 15
	v_lshlrev_b64 v[0:1], 10, v[0:1]
	v_readlane_b32 s37, v251, 16
	s_ashr_i32 s39, s38, 31
	s_add_i32 s31, s31, s92
	v_lshl_add_u64 v[0:1], s[36:37], 0, v[0:1]
	s_add_i32 s30, s30, s33
	v_lshl_add_u64 v[0:1], s[38:39], 1, v[0:1]
	s_cmpk_lt_i32 s31, 0x80
	v_lshl_add_u64 v[0:1], v[0:1], 0, v[96:97]
	s_waitcnt vmcnt(3)
	ds_write2_b32 v5, v8, v9 offset1:1
	ds_write2_b32 v5, v10, v11 offset0:2 offset1:3
	s_waitcnt vmcnt(2)
	ds_write2_b32 v7, v12, v13 offset1:1
	ds_write2_b32 v16, v14, v15 offset1:1
	s_waitcnt lgkmcnt(0)
	s_barrier
	ds_read2_b32 v[8:9], v6 offset1:65
	ds_read2_b32 v[10:11], v6 offset0:130 offset1:195
	ds_read2_b32 v[12:13], v17 offset0:4 offset1:69
	ds_read2_b32 v[14:15], v17 offset0:134 offset1:199
	s_waitcnt lgkmcnt(3)
	v_cvt_pk_bf16_f32 v8, v8, v9
	s_waitcnt lgkmcnt(2)
	v_cvt_pk_bf16_f32 v9, v10, v11
	s_waitcnt lgkmcnt(1)
	v_cvt_pk_bf16_f32 v10, v12, v13
	s_waitcnt lgkmcnt(0)
	v_cvt_pk_bf16_f32 v11, v14, v15
	global_store_dwordx4 v[0:1], v[8:11], off
	s_barrier
	s_cbranch_scc0 .LBB0_743
